# conv_mat loops: loop-top wait counted (vmcnt(4), stores of previous item stay in flight), full wait peeled to preheader; on top of best stack
# baseline (speedup 1.0000x reference)
; #define LAS __attribute__((address_space(3)))
; #define CONV_LOAD(it_) do { const int kb_ = (it_) / nblk, nb_ = (it_) % nblk; _Pragma("unroll") for (int i = 0; i < 8; ++i) { const int k_ = 64 * kb_ + 8 * i + (lane >> 3), n_ = 32 * nb_ + (lane & 7) * 4; \
;         nv[i] = (k_ < K && 32 * nb_ < N) ? *(const f32x4*)(W + (size_t)k_ * N + n_) : (f32x4){0.f, 0.f, 0.f, 0.f}; } } while (0)
; __device__ __forceinline__ void conv_mat(const float* W, int K, int N, bf16_t* WT, int Kp, int Np, LAS float* scr, int gw, int ngw, int lane) {
;     ...
;     if (gw < nitems) CONV_LOAD(gw);
;     for (int item = gw; item < nitems; item += ngw) {
;         const int kb = item / nblk, nb = item % nblk, k0 = 64 * kb, n0 = 32 * nb;
; #pragma unroll
;         for (int i = 0; i < 8; ++i) { const int kk = 8 * i + (lane >> 3), n4 = (lane & 7) * 4; LAS float* d = scr + kk * 33 + n4; d[0] = nv[i][0]; d[1] = nv[i][1]; d[2] = nv[i][2]; d[3] = nv[i][3]; }
;         if (item + ngw < nitems) CONV_LOAD(item + ngw);
;         asm volatile("s_waitcnt lgkmcnt(0)" ::: "memory");
;         const int c = lane & 7;
; #pragma unroll
;         for (int j = 0; j < 4; ++j) { const int n = (lane >> 3) + 8 * j; const LAS float* s = scr + (8 * c) * 33 + n;
.LBB0_38:
	s_or_b64 exec, exec, s[8:9]
	v_lshlrev_b32_e32 v0, 3, v40
	v_and_b32_e32 v0, 56, v0
	v_readlane_b32 s8, v235, 30
	v_lshlrev_b32_e32 v2, 1, v0
	v_readlane_b32 s9, v235, 31
	v_mul_u32_u24_e32 v37, 0x84, v0
	v_lshl_add_u32 v36, v38, 2, s20
	v_lshl_add_u64 v[0:1], s[8:9], 0, v[2:3]
	v_lshlrev_b32_e32 v2, 2, v41
	v_add3_u32 v2, s20, v37, v2
	v_mul_u32_u24_e32 v37, 0x84, v41
	s_lshl_b32 s12, s19, 5
	s_lshl_b32 s13, s18, 5
	v_or_b32_e32 v42, s12, v38
	v_add_u32_e32 v43, v36, v37
	s_mov_b32 s14, s13
	v_mov_b32_e32 v44, v41
	s_mov_b32 s15, s19
	s_waitcnt vmcnt(0)
	s_branch .LBB0_41

; #define LAS __attribute__((address_space(3)))
; #define CONV_LOAD(it_) do { const int kb_ = (it_) / nblk, nb_ = (it_) % nblk; _Pragma("unroll") for (int i = 0; i < 8; ++i) { const int k_ = 64 * kb_ + 8 * i + (lane >> 3), n_ = 32 * nb_ + (lane & 7) * 4; \
;         nv[i] = (k_ < K && 32 * nb_ < N) ? *(const f32x4*)(W + (size_t)k_ * N + n_) : (f32x4){0.f, 0.f, 0.f, 0.f}; } } while (0)
; __device__ __forceinline__ void conv_mat(const float* W, int K, int N, bf16_t* WT, int Kp, int Np, LAS float* scr, int gw, int ngw, int lane) {
;     ...
;     for (int item = gw; item < nitems; item += ngw) {
;         const int kb = item / nblk, nb = item % nblk, k0 = 64 * kb, n0 = 32 * nb;
; #pragma unroll
;         for (int i = 0; i < 8; ++i) { const int kk = 8 * i + (lane >> 3), n4 = (lane & 7) * 4; LAS float* d = scr + kk * 33 + n4; d[0] = nv[i][0]; d[1] = nv[i][1]; d[2] = nv[i][2]; d[3] = nv[i][3]; }
;         if (item + ngw < nitems) CONV_LOAD(item + ngw);
.LBB0_41:
	v_add_u32_e32 v36, 0x420, v43
	s_waitcnt vmcnt(4)
	ds_write2_b32 v43, v8, v9 offset1:1
	ds_write2_b32 v43, v10, v11 offset0:2 offset1:3
	ds_write2_b32 v36, v4, v5 offset1:1
	v_add_u32_e32 v36, 0x428, v43
	ds_write2_b32 v36, v6, v7 offset1:1
	v_add_u32_e32 v36, 0x840, v43
	ds_write2_b32 v36, v16, v17 offset1:1
	v_add_u32_e32 v36, 0x848, v43
	ds_write2_b32 v36, v18, v19 offset1:1
	v_add_u32_e32 v36, 0xc60, v43
	ds_write2_b32 v36, v12, v13 offset1:1
	v_add_u32_e32 v36, 0xc68, v43
	ds_write2_b32 v36, v14, v15 offset1:1
	v_add_u32_e32 v36, 0x1080, v43
	ds_write2_b32 v36, v24, v25 offset1:1
	v_add_u32_e32 v36, 0x1088, v43
	ds_write2_b32 v36, v26, v27 offset1:1
	v_add_u32_e32 v36, 0x14a0, v43
	ds_write2_b32 v36, v20, v21 offset1:1
	v_add_u32_e32 v36, 0x14a8, v43
	ds_write2_b32 v36, v22, v23 offset1:1
	v_add_u32_e32 v36, 0x18c0, v43
	s_add_i32 s16, s15, s18
	ds_write2_b32 v36, v32, v33 offset1:1
	v_add_u32_e32 v36, 0x18c8, v43
	s_cmpk_gt_i32 s16, 0x1fff
	ds_write2_b32 v36, v34, v35 offset1:1
	v_add_u32_e32 v36, 0x1ce0, v43
	s_cselect_b64 s[8:9], -1, 0
	ds_write2_b32 v36, v28, v29 offset1:1
	v_add_u32_e32 v36, 0x1ce8, v43
	s_and_b64 vcc, exec, s[8:9]
	ds_write2_b32 v36, v30, v31 offset1:1
	s_cbranch_vccnz .LBB0_40
	s_ashr_i32 s10, s16, 31
	s_lshr_b32 s10, s10, 24
	s_add_i32 s10, s16, s10
	s_ashr_i32 s10, s10, 8
	v_lshl_or_b32 v30, s10, 6, v41
	v_add_u32_e32 v4, s14, v42
	s_lshl_b32 s10, s10, 13
	v_subrev_u32_e32 v4, s10, v4
	v_ashrrev_i32_e32 v5, 31, v4
	v_lshl_add_u64 v[36:37], v[4:5], 2, s[4:5]
	v_cmp_gt_i32_e32 vcc, s50, v30
	v_mov_b32_e32 v4, 0
	v_mov_b32_e32 v8, 0
	v_mov_b32_e32 v9, 0
	v_mov_b32_e32 v10, 0
	v_mov_b32_e32 v11, 0
	s_and_saveexec_b64 s[10:11], vcc
	s_cbranch_execz .LBB0_44
	v_ashrrev_i32_e32 v31, 31, v30
	v_lshlrev_b64 v[6:7], 15, v[30:31]
	v_lshl_add_u64 v[6:7], v[36:37], 0, v[6:7]
	global_load_dwordx4 v[8:11], v[6:7], off

; #define LAS __attribute__((address_space(3)))
; #define CONV_LOAD(it_) do { const int kb_ = (it_) / nblk, nb_ = (it_) % nblk; _Pragma("unroll") for (int i = 0; i < 8; ++i) { const int k_ = 64 * kb_ + 8 * i + (lane >> 3), n_ = 32 * nb_ + (lane & 7) * 4; \
;         nv[i] = (k_ < K && 32 * nb_ < N) ? *(const f32x4*)(W + (size_t)k_ * N + n_) : (f32x4){0.f, 0.f, 0.f, 0.f}; } } while (0)
; __device__ __forceinline__ void conv_mat(const float* W, int K, int N, bf16_t* WT, int Kp, int Np, LAS float* scr, int gw, int ngw, int lane) {
;     ...
;     if (gw < nitems) CONV_LOAD(gw);
;     for (int item = gw; item < nitems; item += ngw) {
;         const int kb = item / nblk, nb = item % nblk, k0 = 64 * kb, n0 = 32 * nb;
; #pragma unroll
;         for (int i = 0; i < 8; ++i) { const int kk = 8 * i + (lane >> 3), n4 = (lane & 7) * 4; LAS float* d = scr + kk * 33 + n4; d[0] = nv[i][0]; d[1] = nv[i][1]; d[2] = nv[i][2]; d[3] = nv[i][3]; }
;         if (item + ngw < nitems) CONV_LOAD(item + ngw);
;         asm volatile("s_waitcnt lgkmcnt(0)" ::: "memory");
;         const int c = lane & 7;
; #pragma unroll
;         for (int j = 0; j < 4; ++j) { const int n = (lane >> 3) + 8 * j; const LAS float* s = scr + (8 * c) * 33 + n;
.LBB0_75:
	s_or_b64 exec, exec, s[4:5]
	v_lshlrev_b32_e32 v0, 3, v40
	v_and_b32_e32 v0, 56, v0
	v_readlane_b32 s4, v235, 4
	v_lshlrev_b32_e32 v2, 1, v0
	v_readlane_b32 s5, v235, 5
	v_mul_u32_u24_e32 v37, 0x84, v0
	v_lshl_add_u32 v36, v38, 2, s20
	v_lshl_add_u64 v[0:1], s[4:5], 0, v[2:3]
	v_lshlrev_b32_e32 v2, 2, v41
	v_add3_u32 v2, s20, v37, v2
	v_mul_u32_u24_e32 v37, 0x84, v41
	s_lshl_b32 s10, s19, 5
	s_lshl_b32 s11, s18, 5
	v_or_b32_e32 v42, s10, v38
	v_add_u32_e32 v43, v36, v37
	s_mov_b32 s12, s11
	v_mov_b32_e32 v44, v41
	s_mov_b32 s13, s19
	s_waitcnt vmcnt(0)
	s_branch .LBB0_78

; #define LAS __attribute__((address_space(3)))
; #define CONV_LOAD(it_) do { const int kb_ = (it_) / nblk, nb_ = (it_) % nblk; _Pragma("unroll") for (int i = 0; i < 8; ++i) { const int k_ = 64 * kb_ + 8 * i + (lane >> 3), n_ = 32 * nb_ + (lane & 7) * 4; \
;         nv[i] = (k_ < K && 32 * nb_ < N) ? *(const f32x4*)(W + (size_t)k_ * N + n_) : (f32x4){0.f, 0.f, 0.f, 0.f}; } } while (0)
; __device__ __forceinline__ void conv_mat(const float* W, int K, int N, bf16_t* WT, int Kp, int Np, LAS float* scr, int gw, int ngw, int lane) {
;     ...
;     for (int item = gw; item < nitems; item += ngw) {
;         const int kb = item / nblk, nb = item % nblk, k0 = 64 * kb, n0 = 32 * nb;
; #pragma unroll
;         for (int i = 0; i < 8; ++i) { const int kk = 8 * i + (lane >> 3), n4 = (lane & 7) * 4; LAS float* d = scr + kk * 33 + n4; d[0] = nv[i][0]; d[1] = nv[i][1]; d[2] = nv[i][2]; d[3] = nv[i][3]; }
;         if (item + ngw < nitems) CONV_LOAD(item + ngw);
.LBB0_78:
	v_add_u32_e32 v36, 0x420, v43
	s_waitcnt vmcnt(4)
	ds_write2_b32 v43, v8, v9 offset1:1
	ds_write2_b32 v43, v10, v11 offset0:2 offset1:3
	ds_write2_b32 v36, v4, v5 offset1:1
	v_add_u32_e32 v36, 0x428, v43
	ds_write2_b32 v36, v6, v7 offset1:1
	v_add_u32_e32 v36, 0x840, v43
	ds_write2_b32 v36, v16, v17 offset1:1
	v_add_u32_e32 v36, 0x848, v43
	ds_write2_b32 v36, v18, v19 offset1:1
	v_add_u32_e32 v36, 0xc60, v43
	ds_write2_b32 v36, v12, v13 offset1:1
	v_add_u32_e32 v36, 0xc68, v43
	ds_write2_b32 v36, v14, v15 offset1:1
	v_add_u32_e32 v36, 0x1080, v43
	ds_write2_b32 v36, v24, v25 offset1:1
	v_add_u32_e32 v36, 0x1088, v43
	ds_write2_b32 v36, v26, v27 offset1:1
	v_add_u32_e32 v36, 0x14a0, v43
	ds_write2_b32 v36, v20, v21 offset1:1
	v_add_u32_e32 v36, 0x14a8, v43
	ds_write2_b32 v36, v22, v23 offset1:1
	v_add_u32_e32 v36, 0x18c0, v43
	s_add_i32 s14, s13, s18
	ds_write2_b32 v36, v32, v33 offset1:1
	v_add_u32_e32 v36, 0x18c8, v43
	s_cmpk_gt_i32 s14, 0x1fff
	ds_write2_b32 v36, v34, v35 offset1:1
	v_add_u32_e32 v36, 0x1ce0, v43
	s_cselect_b64 s[4:5], -1, 0
	ds_write2_b32 v36, v28, v29 offset1:1
	v_add_u32_e32 v36, 0x1ce8, v43
	s_and_b64 vcc, exec, s[4:5]
	ds_write2_b32 v36, v30, v31 offset1:1
	s_cbranch_vccnz .LBB0_77
	s_ashr_i32 s8, s14, 31
	s_lshr_b32 s8, s8, 26
	s_add_i32 s8, s14, s8
	s_and_b32 s9, s8, 0xffffffc0
	s_lshl_b32 s8, s8, 5
	v_add_u32_e32 v4, s12, v42
	s_and_b32 s8, s8, 0xfffff800
	v_subrev_u32_e32 v4, s8, v4
	v_or_b32_e32 v30, s9, v41
	v_ashrrev_i32_e32 v5, 31, v4
	s_movk_i32 s8, 0x2000
	v_lshl_add_u64 v[36:37], v[4:5], 2, s[2:3]
	v_cmp_gt_i32_e32 vcc, s8, v30
	v_mov_b32_e32 v4, 0
	v_mov_b32_e32 v8, 0
	v_mov_b32_e32 v9, 0
	v_mov_b32_e32 v10, 0
	v_mov_b32_e32 v11, 0
	s_and_saveexec_b64 s[8:9], vcc
	s_cbranch_execz .LBB0_81
	v_ashrrev_i32_e32 v31, 31, v30
	v_lshlrev_b64 v[6:7], 13, v[30:31]
	v_lshl_add_u64 v[6:7], v[36:37], 0, v[6:7]
	global_load_dwordx4 v[8:11], v[6:7], off

; #define LAS __attribute__((address_space(3)))
; #define CONV_LOAD(it_) do { const int kb_ = (it_) / nblk, nb_ = (it_) % nblk; _Pragma("unroll") for (int i = 0; i < 8; ++i) { const int k_ = 64 * kb_ + 8 * i + (lane >> 3), n_ = 32 * nb_ + (lane & 7) * 4; \
;         nv[i] = (k_ < K && 32 * nb_ < N) ? *(const f32x4*)(W + (size_t)k_ * N + n_) : (f32x4){0.f, 0.f, 0.f, 0.f}; } } while (0)
; __device__ __forceinline__ void conv_mat(const float* W, int K, int N, bf16_t* WT, int Kp, int Np, LAS float* scr, int gw, int ngw, int lane) {
;     ...
;     if (gw < nitems) CONV_LOAD(gw);
;     for (int item = gw; item < nitems; item += ngw) {
;         const int kb = item / nblk, nb = item % nblk, k0 = 64 * kb, n0 = 32 * nb;
; #pragma unroll
;         for (int i = 0; i < 8; ++i) { const int kk = 8 * i + (lane >> 3), n4 = (lane & 7) * 4; LAS float* d = scr + kk * 33 + n4; d[0] = nv[i][0]; d[1] = nv[i][1]; d[2] = nv[i][2]; d[3] = nv[i][3]; }
;         if (item + ngw < nitems) CONV_LOAD(item + ngw);
;         asm volatile("s_waitcnt lgkmcnt(0)" ::: "memory");
;         const int c = lane & 7;
; #pragma unroll
;         for (int j = 0; j < 4; ++j) { const int n = (lane >> 3) + 8 * j; const LAS float* s = scr + (8 * c) * 33 + n;
.LBB0_113:
	s_or_b64 exec, exec, s[12:13]
	v_lshlrev_b32_e32 v0, 3, v40
	v_and_b32_e32 v0, 56, v0
	v_readlane_b32 s12, v235, 6
	v_lshlrev_b32_e32 v2, 1, v0
	v_readlane_b32 s13, v235, 7
	v_mul_u32_u24_e32 v37, 0x84, v0
	v_lshl_add_u32 v36, v38, 2, s20
	v_lshl_add_u64 v[0:1], s[12:13], 0, v[2:3]
	v_lshlrev_b32_e32 v2, 2, v41
	v_add3_u32 v2, s20, v37, v2
	v_mul_u32_u24_e32 v37, 0x84, v41
	s_lshl_b32 s16, s19, 5
	s_lshl_b32 s17, s18, 5
	v_or_b32_e32 v42, s16, v38
	v_add_u32_e32 v43, v36, v37
	s_mov_b32 s21, s17
	v_mov_b32_e32 v44, v41
	s_mov_b32 s22, s19
	s_waitcnt vmcnt(0)
	s_branch .LBB0_116

; #define LAS __attribute__((address_space(3)))
; #define CONV_LOAD(it_) do { const int kb_ = (it_) / nblk, nb_ = (it_) % nblk; _Pragma("unroll") for (int i = 0; i < 8; ++i) { const int k_ = 64 * kb_ + 8 * i + (lane >> 3), n_ = 32 * nb_ + (lane & 7) * 4; \
;         nv[i] = (k_ < K && 32 * nb_ < N) ? *(const f32x4*)(W + (size_t)k_ * N + n_) : (f32x4){0.f, 0.f, 0.f, 0.f}; } } while (0)
; __device__ __forceinline__ void conv_mat(const float* W, int K, int N, bf16_t* WT, int Kp, int Np, LAS float* scr, int gw, int ngw, int lane) {
;     ...
;     for (int item = gw; item < nitems; item += ngw) {
;         const int kb = item / nblk, nb = item % nblk, k0 = 64 * kb, n0 = 32 * nb;
; #pragma unroll
;         for (int i = 0; i < 8; ++i) { const int kk = 8 * i + (lane >> 3), n4 = (lane & 7) * 4; LAS float* d = scr + kk * 33 + n4; d[0] = nv[i][0]; d[1] = nv[i][1]; d[2] = nv[i][2]; d[3] = nv[i][3]; }
;         if (item + ngw < nitems) CONV_LOAD(item + ngw);
.LBB0_116:
	v_add_u32_e32 v36, 0x420, v43
	s_waitcnt vmcnt(4)
	ds_write2_b32 v43, v8, v9 offset1:1
	ds_write2_b32 v43, v10, v11 offset0:2 offset1:3
	ds_write2_b32 v36, v4, v5 offset1:1
	v_add_u32_e32 v36, 0x428, v43
	ds_write2_b32 v36, v6, v7 offset1:1
	v_add_u32_e32 v36, 0x840, v43
	ds_write2_b32 v36, v16, v17 offset1:1
	v_add_u32_e32 v36, 0x848, v43
	ds_write2_b32 v36, v18, v19 offset1:1
	v_add_u32_e32 v36, 0xc60, v43
	ds_write2_b32 v36, v12, v13 offset1:1
	v_add_u32_e32 v36, 0xc68, v43
	ds_write2_b32 v36, v14, v15 offset1:1
	v_add_u32_e32 v36, 0x1080, v43
	ds_write2_b32 v36, v24, v25 offset1:1
	v_add_u32_e32 v36, 0x1088, v43
	ds_write2_b32 v36, v26, v27 offset1:1
	v_add_u32_e32 v36, 0x14a0, v43
	ds_write2_b32 v36, v20, v21 offset1:1
	v_add_u32_e32 v36, 0x14a8, v43
	ds_write2_b32 v36, v22, v23 offset1:1
	v_add_u32_e32 v36, 0x18c0, v43
	s_add_i32 s23, s22, s18
	ds_write2_b32 v36, v32, v33 offset1:1
	v_add_u32_e32 v36, 0x18c8, v43
	s_cmpk_gt_i32 s23, 0x7ff
	ds_write2_b32 v36, v34, v35 offset1:1
	v_add_u32_e32 v36, 0x1ce0, v43
	s_cselect_b64 s[12:13], -1, 0
	ds_write2_b32 v36, v28, v29 offset1:1
	v_add_u32_e32 v36, 0x1ce8, v43
	s_and_b64 vcc, exec, s[12:13]
	ds_write2_b32 v36, v30, v31 offset1:1
	s_cbranch_vccnz .LBB0_115
	s_ashr_i32 s14, s23, 31
	s_lshr_b32 s14, s14, 26
	s_add_i32 s14, s23, s14
	s_and_b32 s15, s14, 0xffffffc0
	s_lshl_b32 s14, s14, 5
	v_add_u32_e32 v4, s21, v42
	s_and_b32 s14, s14, 0xfffff800
	v_subrev_u32_e32 v4, s14, v4
	v_or_b32_e32 v30, s15, v41
	v_ashrrev_i32_e32 v5, 31, v4
	v_lshl_add_u64 v[36:37], v[4:5], 2, s[4:5]
	v_cmp_gt_i32_e32 vcc, s50, v30
	v_mov_b32_e32 v4, 0
	v_mov_b32_e32 v8, 0
	v_mov_b32_e32 v9, 0
	v_mov_b32_e32 v10, 0
	v_mov_b32_e32 v11, 0
	s_and_saveexec_b64 s[14:15], vcc
	s_cbranch_execz .LBB0_119
	v_ashrrev_i32_e32 v31, 31, v30
	v_lshlrev_b64 v[6:7], 13, v[30:31]
	v_lshl_add_u64 v[6:7], v[36:37], 0, v[6:7]
	global_load_dwordx4 v[8:11], v[6:7], off

; #define LAS __attribute__((address_space(3)))
; #define CONV_LOAD(it_) do { const int kb_ = (it_) / nblk, nb_ = (it_) % nblk; _Pragma("unroll") for (int i = 0; i < 8; ++i) { const int k_ = 64 * kb_ + 8 * i + (lane >> 3), n_ = 32 * nb_ + (lane & 7) * 4; \
;         nv[i] = (k_ < K && 32 * nb_ < N) ? *(const f32x4*)(W + (size_t)k_ * N + n_) : (f32x4){0.f, 0.f, 0.f, 0.f}; } } while (0)
; __device__ __forceinline__ void conv_mat(const float* W, int K, int N, bf16_t* WT, int Kp, int Np, LAS float* scr, int gw, int ngw, int lane) {
;     ...
;     if (gw < nitems) CONV_LOAD(gw);
;     for (int item = gw; item < nitems; item += ngw) {
;         const int kb = item / nblk, nb = item % nblk, k0 = 64 * kb, n0 = 32 * nb;
; #pragma unroll
;         for (int i = 0; i < 8; ++i) { const int kk = 8 * i + (lane >> 3), n4 = (lane & 7) * 4; LAS float* d = scr + kk * 33 + n4; d[0] = nv[i][0]; d[1] = nv[i][1]; d[2] = nv[i][2]; d[3] = nv[i][3]; }
;         if (item + ngw < nitems) CONV_LOAD(item + ngw);
;         asm volatile("s_waitcnt lgkmcnt(0)" ::: "memory");
;         const int c = lane & 7;
; #pragma unroll
;         for (int j = 0; j < 4; ++j) { const int n = (lane >> 3) + 8 * j; const LAS float* s = scr + (8 * c) * 33 + n;
.LBB0_150:
	s_or_b64 exec, exec, s[12:13]
	v_lshlrev_b32_e32 v0, 3, v40
	v_and_b32_e32 v0, 56, v0
	v_readlane_b32 s12, v235, 8
	v_lshlrev_b32_e32 v2, 1, v0
	v_readlane_b32 s13, v235, 9
	v_mul_u32_u24_e32 v37, 0x84, v0
	v_lshl_add_u32 v36, v38, 2, s20
	v_lshl_add_u64 v[0:1], s[12:13], 0, v[2:3]
	v_lshlrev_b32_e32 v2, 2, v41
	v_add3_u32 v2, s20, v37, v2
	v_mul_u32_u24_e32 v37, 0x84, v41
	s_lshl_b32 s16, s19, 5
	s_lshl_b32 s17, s18, 5
	v_or_b32_e32 v42, s16, v38
	v_add_u32_e32 v43, v36, v37
	s_mov_b32 s21, s17
	v_mov_b32_e32 v44, v41
	s_mov_b32 s22, s19
	s_waitcnt vmcnt(0)
	s_branch .LBB0_153

; #define LAS __attribute__((address_space(3)))
; #define CONV_LOAD(it_) do { const int kb_ = (it_) / nblk, nb_ = (it_) % nblk; _Pragma("unroll") for (int i = 0; i < 8; ++i) { const int k_ = 64 * kb_ + 8 * i + (lane >> 3), n_ = 32 * nb_ + (lane & 7) * 4; \
;         nv[i] = (k_ < K && 32 * nb_ < N) ? *(const f32x4*)(W + (size_t)k_ * N + n_) : (f32x4){0.f, 0.f, 0.f, 0.f}; } } while (0)
; __device__ __forceinline__ void conv_mat(const float* W, int K, int N, bf16_t* WT, int Kp, int Np, LAS float* scr, int gw, int ngw, int lane) {
;     ...
;     for (int item = gw; item < nitems; item += ngw) {
;         const int kb = item / nblk, nb = item % nblk, k0 = 64 * kb, n0 = 32 * nb;
; #pragma unroll
;         for (int i = 0; i < 8; ++i) { const int kk = 8 * i + (lane >> 3), n4 = (lane & 7) * 4; LAS float* d = scr + kk * 33 + n4; d[0] = nv[i][0]; d[1] = nv[i][1]; d[2] = nv[i][2]; d[3] = nv[i][3]; }
;         if (item + ngw < nitems) CONV_LOAD(item + ngw);
.LBB0_153:
	v_add_u32_e32 v36, 0x420, v43
	s_waitcnt vmcnt(4)
	ds_write2_b32 v43, v8, v9 offset1:1
	ds_write2_b32 v43, v10, v11 offset0:2 offset1:3
	ds_write2_b32 v36, v4, v5 offset1:1
	v_add_u32_e32 v36, 0x428, v43
	ds_write2_b32 v36, v6, v7 offset1:1
	v_add_u32_e32 v36, 0x840, v43
	ds_write2_b32 v36, v16, v17 offset1:1
	v_add_u32_e32 v36, 0x848, v43
	ds_write2_b32 v36, v18, v19 offset1:1
	v_add_u32_e32 v36, 0xc60, v43
	ds_write2_b32 v36, v12, v13 offset1:1
	v_add_u32_e32 v36, 0xc68, v43
	ds_write2_b32 v36, v14, v15 offset1:1
	v_add_u32_e32 v36, 0x1080, v43
	ds_write2_b32 v36, v24, v25 offset1:1
	v_add_u32_e32 v36, 0x1088, v43
	ds_write2_b32 v36, v26, v27 offset1:1
	v_add_u32_e32 v36, 0x14a0, v43
	ds_write2_b32 v36, v20, v21 offset1:1
	v_add_u32_e32 v36, 0x14a8, v43
	ds_write2_b32 v36, v22, v23 offset1:1
	v_add_u32_e32 v36, 0x18c0, v43
	s_add_i32 s23, s22, s18
	ds_write2_b32 v36, v32, v33 offset1:1
	v_add_u32_e32 v36, 0x18c8, v43
	s_cmpk_gt_i32 s23, 0x7ff
	ds_write2_b32 v36, v34, v35 offset1:1
	v_add_u32_e32 v36, 0x1ce0, v43
	s_cselect_b64 s[12:13], -1, 0
	ds_write2_b32 v36, v28, v29 offset1:1
	v_add_u32_e32 v36, 0x1ce8, v43
	s_and_b64 vcc, exec, s[12:13]
	ds_write2_b32 v36, v30, v31 offset1:1
	s_cbranch_vccnz .LBB0_152
	s_ashr_i32 s14, s23, 31
	s_lshr_b32 s14, s14, 26
	s_add_i32 s14, s23, s14
	s_and_b32 s15, s14, 0xffffffc0
	s_lshl_b32 s14, s14, 5
	v_add_u32_e32 v4, s21, v42
	s_and_b32 s14, s14, 0xfffff800
	v_subrev_u32_e32 v4, s14, v4
	v_or_b32_e32 v30, s15, v41
	v_ashrrev_i32_e32 v5, 31, v4
	v_lshl_add_u64 v[36:37], v[4:5], 2, s[10:11]
	v_cmp_gt_i32_e32 vcc, s50, v30
	v_mov_b32_e32 v4, 0
	v_mov_b32_e32 v8, 0
	v_mov_b32_e32 v9, 0
	v_mov_b32_e32 v10, 0
	v_mov_b32_e32 v11, 0
	s_and_saveexec_b64 s[14:15], vcc
	s_cbranch_execz .LBB0_156
	v_ashrrev_i32_e32 v31, 31, v30
	v_lshlrev_b64 v[6:7], 13, v[30:31]
	v_lshl_add_u64 v[6:7], v[36:37], 0, v[6:7]
	global_load_dwordx4 v[8:11], v[6:7], off

; #define LAS __attribute__((address_space(3)))
; #define CONV_LOAD(it_) do { const int kb_ = (it_) / nblk, nb_ = (it_) % nblk; _Pragma("unroll") for (int i = 0; i < 8; ++i) { const int k_ = 64 * kb_ + 8 * i + (lane >> 3), n_ = 32 * nb_ + (lane & 7) * 4; \
;         nv[i] = (k_ < K && 32 * nb_ < N) ? *(const f32x4*)(W + (size_t)k_ * N + n_) : (f32x4){0.f, 0.f, 0.f, 0.f}; } } while (0)
; __device__ __forceinline__ void conv_mat(const float* W, int K, int N, bf16_t* WT, int Kp, int Np, LAS float* scr, int gw, int ngw, int lane) {
;     ...
;     if (gw < nitems) CONV_LOAD(gw);
;     for (int item = gw; item < nitems; item += ngw) {
;         const int kb = item / nblk, nb = item % nblk, k0 = 64 * kb, n0 = 32 * nb;
; #pragma unroll
;         for (int i = 0; i < 8; ++i) { const int kk = 8 * i + (lane >> 3), n4 = (lane & 7) * 4; LAS float* d = scr + kk * 33 + n4; d[0] = nv[i][0]; d[1] = nv[i][1]; d[2] = nv[i][2]; d[3] = nv[i][3]; }
;         if (item + ngw < nitems) CONV_LOAD(item + ngw);
;         asm volatile("s_waitcnt lgkmcnt(0)" ::: "memory");
;         const int c = lane & 7;
; #pragma unroll
;         for (int j = 0; j < 4; ++j) { const int n = (lane >> 3) + 8 * j; const LAS float* s = scr + (8 * c) * 33 + n;
.LBB0_187:
	s_or_b64 exec, exec, s[12:13]
	v_lshlrev_b32_e32 v0, 3, v40
	v_and_b32_e32 v0, 56, v0
	v_readlane_b32 s12, v235, 10
	v_lshlrev_b32_e32 v2, 1, v0
	v_readlane_b32 s13, v235, 11
	v_mul_u32_u24_e32 v37, 0x84, v0
	v_lshl_add_u32 v36, v38, 2, s20
	v_lshl_add_u64 v[0:1], s[12:13], 0, v[2:3]
	v_lshlrev_b32_e32 v2, 2, v41
	v_add3_u32 v2, s20, v37, v2
	v_mul_u32_u24_e32 v37, 0x84, v41
	s_lshl_b32 s16, s19, 5
	s_lshl_b32 s17, s18, 5
	v_or_b32_e32 v42, s16, v38
	v_add_u32_e32 v43, v36, v37
	s_mov_b32 s21, s17
	v_mov_b32_e32 v44, v41
	s_mov_b32 s22, s19
	s_waitcnt vmcnt(0)
	s_branch .LBB0_190

; #define LAS __attribute__((address_space(3)))
; #define CONV_LOAD(it_) do { const int kb_ = (it_) / nblk, nb_ = (it_) % nblk; _Pragma("unroll") for (int i = 0; i < 8; ++i) { const int k_ = 64 * kb_ + 8 * i + (lane >> 3), n_ = 32 * nb_ + (lane & 7) * 4; \
;         nv[i] = (k_ < K && 32 * nb_ < N) ? *(const f32x4*)(W + (size_t)k_ * N + n_) : (f32x4){0.f, 0.f, 0.f, 0.f}; } } while (0)
; __device__ __forceinline__ void conv_mat(const float* W, int K, int N, bf16_t* WT, int Kp, int Np, LAS float* scr, int gw, int ngw, int lane) {
;     ...
;     if (gw < nitems) CONV_LOAD(gw);
;     for (int item = gw; item < nitems; item += ngw) {
;         const int kb = item / nblk, nb = item % nblk, k0 = 64 * kb, n0 = 32 * nb;
; #pragma unroll
;         for (int i = 0; i < 8; ++i) { const int kk = 8 * i + (lane >> 3), n4 = (lane & 7) * 4; LAS float* d = scr + kk * 33 + n4; d[0] = nv[i][0]; d[1] = nv[i][1]; d[2] = nv[i][2]; d[3] = nv[i][3]; }
;         if (item + ngw < nitems) CONV_LOAD(item + ngw);
;         asm volatile("s_waitcnt lgkmcnt(0)" ::: "memory");
;         const int c = lane & 7;
; #pragma unroll
;         for (int j = 0; j < 4; ++j) { const int n = (lane >> 3) + 8 * j; const LAS float* s = scr + (8 * c) * 33 + n;
.LBB0_224:
	s_or_b64 exec, exec, s[4:5]
	v_lshlrev_b32_e32 v0, 3, v40
	v_and_b32_e32 v0, 56, v0
	v_readlane_b32 s4, v235, 12
	v_lshlrev_b32_e32 v2, 1, v0
	v_readlane_b32 s5, v235, 13
	v_mul_u32_u24_e32 v37, 0x84, v0
	v_lshl_add_u32 v36, v38, 2, s20
	v_lshl_add_u64 v[0:1], s[4:5], 0, v[2:3]
	v_lshlrev_b32_e32 v2, 2, v41
	v_add3_u32 v2, s20, v37, v2
	v_mul_u32_u24_e32 v37, 0x84, v41
	s_lshl_b32 s12, s19, 5
	s_lshl_b32 s13, s18, 5
	v_or_b32_e32 v42, s12, v38
	v_add_u32_e32 v43, v36, v37
	s_mov_b32 s14, s13
	v_mov_b32_e32 v44, v41
	s_mov_b32 s15, s19
	s_waitcnt vmcnt(0)
	s_branch .LBB0_227

; #define LAS __attribute__((address_space(3)))
; #define CONV_LOAD(it_) do { const int kb_ = (it_) / nblk, nb_ = (it_) % nblk; _Pragma("unroll") for (int i = 0; i < 8; ++i) { const int k_ = 64 * kb_ + 8 * i + (lane >> 3), n_ = 32 * nb_ + (lane & 7) * 4; \
;         nv[i] = (k_ < K && 32 * nb_ < N) ? *(const f32x4*)(W + (size_t)k_ * N + n_) : (f32x4){0.f, 0.f, 0.f, 0.f}; } } while (0)
; __device__ __forceinline__ void conv_mat(const float* W, int K, int N, bf16_t* WT, int Kp, int Np, LAS float* scr, int gw, int ngw, int lane) {
;     ...
;     for (int item = gw; item < nitems; item += ngw) {
;         const int kb = item / nblk, nb = item % nblk, k0 = 64 * kb, n0 = 32 * nb;
; #pragma unroll
;         for (int i = 0; i < 8; ++i) { const int kk = 8 * i + (lane >> 3), n4 = (lane & 7) * 4; LAS float* d = scr + kk * 33 + n4; d[0] = nv[i][0]; d[1] = nv[i][1]; d[2] = nv[i][2]; d[3] = nv[i][3]; }
;         if (item + ngw < nitems) CONV_LOAD(item + ngw);
.LBB0_227:
	v_add_u32_e32 v36, 0x420, v43
	s_waitcnt vmcnt(4)
	ds_write2_b32 v43, v8, v9 offset1:1
	ds_write2_b32 v43, v10, v11 offset0:2 offset1:3
	ds_write2_b32 v36, v4, v5 offset1:1
	v_add_u32_e32 v36, 0x428, v43
	ds_write2_b32 v36, v6, v7 offset1:1
	v_add_u32_e32 v36, 0x840, v43
	ds_write2_b32 v36, v16, v17 offset1:1
	v_add_u32_e32 v36, 0x848, v43
	ds_write2_b32 v36, v18, v19 offset1:1
	v_add_u32_e32 v36, 0xc60, v43
	ds_write2_b32 v36, v12, v13 offset1:1
	v_add_u32_e32 v36, 0xc68, v43
	ds_write2_b32 v36, v14, v15 offset1:1
	v_add_u32_e32 v36, 0x1080, v43
	ds_write2_b32 v36, v24, v25 offset1:1
	v_add_u32_e32 v36, 0x1088, v43
	ds_write2_b32 v36, v26, v27 offset1:1
	v_add_u32_e32 v36, 0x14a0, v43
	ds_write2_b32 v36, v20, v21 offset1:1
	v_add_u32_e32 v36, 0x14a8, v43
	ds_write2_b32 v36, v22, v23 offset1:1
	v_add_u32_e32 v36, 0x18c0, v43
	s_add_i32 s16, s15, s18
	ds_write2_b32 v36, v32, v33 offset1:1
	v_add_u32_e32 v36, 0x18c8, v43
	s_cmpk_gt_i32 s16, 0x7ff
	ds_write2_b32 v36, v34, v35 offset1:1
	v_add_u32_e32 v36, 0x1ce0, v43
	s_cselect_b64 s[4:5], -1, 0
	ds_write2_b32 v36, v28, v29 offset1:1
	v_add_u32_e32 v36, 0x1ce8, v43
	s_and_b64 vcc, exec, s[4:5]
	ds_write2_b32 v36, v30, v31 offset1:1
	s_cbranch_vccnz .LBB0_226
	s_ashr_i32 s10, s16, 31
	s_lshr_b32 s10, s10, 26
	s_add_i32 s10, s16, s10
	s_and_b32 s11, s10, 0xffffffc0
	s_lshl_b32 s10, s10, 5
	v_add_u32_e32 v4, s14, v42
	s_and_b32 s10, s10, 0xfffff800
	v_subrev_u32_e32 v4, s10, v4
	v_or_b32_e32 v30, s11, v41
	v_ashrrev_i32_e32 v5, 31, v4
	v_lshl_add_u64 v[36:37], v[4:5], 2, s[2:3]
	v_cmp_gt_i32_e32 vcc, s50, v30
	v_mov_b32_e32 v4, 0
	v_mov_b32_e32 v8, 0
	v_mov_b32_e32 v9, 0
	v_mov_b32_e32 v10, 0
	v_mov_b32_e32 v11, 0
	s_and_saveexec_b64 s[10:11], vcc
	s_cbranch_execz .LBB0_230
	v_ashrrev_i32_e32 v31, 31, v30
	v_lshlrev_b64 v[6:7], 13, v[30:31]
	v_lshl_add_u64 v[6:7], v[36:37], 0, v[6:7]
	global_load_dwordx4 v[8:11], v[6:7], off

; #define LAS __attribute__((address_space(3)))
; #define CONV_LOAD(it_) do { const int kb_ = (it_) / nblk, nb_ = (it_) % nblk; _Pragma("unroll") for (int i = 0; i < 8; ++i) { const int k_ = 64 * kb_ + 8 * i + (lane >> 3), n_ = 32 * nb_ + (lane & 7) * 4; \
;         nv[i] = (k_ < K && 32 * nb_ < N) ? *(const f32x4*)(W + (size_t)k_ * N + n_) : (f32x4){0.f, 0.f, 0.f, 0.f}; } } while (0)
; __device__ __forceinline__ void conv_mat(const float* W, int K, int N, bf16_t* WT, int Kp, int Np, LAS float* scr, int gw, int ngw, int lane) {
;     ...
;     if (gw < nitems) CONV_LOAD(gw);
;     for (int item = gw; item < nitems; item += ngw) {
;         const int kb = item / nblk, nb = item % nblk, k0 = 64 * kb, n0 = 32 * nb;
; #pragma unroll
;         for (int i = 0; i < 8; ++i) { const int kk = 8 * i + (lane >> 3), n4 = (lane & 7) * 4; LAS float* d = scr + kk * 33 + n4; d[0] = nv[i][0]; d[1] = nv[i][1]; d[2] = nv[i][2]; d[3] = nv[i][3]; }
;         if (item + ngw < nitems) CONV_LOAD(item + ngw);
;         asm volatile("s_waitcnt lgkmcnt(0)" ::: "memory");
;         const int c = lane & 7;
; #pragma unroll
;         for (int j = 0; j < 4; ++j) { const int n = (lane >> 3) + 8 * j; const LAS float* s = scr + (8 * c) * 33 + n;
.LBB0_261:
	s_or_b64 exec, exec, s[12:13]
	v_lshlrev_b32_e32 v0, 3, v40
	v_and_b32_e32 v0, 56, v0
	v_readlane_b32 s12, v235, 14
	v_lshlrev_b32_e32 v2, 1, v0
	v_readlane_b32 s13, v235, 15
	v_lshl_add_u32 v37, v36, 2, s20
	v_mul_u32_u24_e32 v39, 0x84, v0
	v_lshl_add_u64 v[0:1], s[12:13], 0, v[2:3]
	v_lshlrev_b32_e32 v2, 2, v38
	v_mul_u32_u24_e32 v41, 0x84, v38
	s_lshl_b32 s21, s19, 5
	s_lshl_b32 s22, s18, 5
	v_add3_u32 v2, s20, v39, v2
	v_or_b32_e32 v39, s21, v36
	v_add_u32_e32 v41, v37, v41
	s_mov_b32 s23, s22
	v_mov_b32_e32 v42, v38
	s_mov_b32 s24, s19
	s_waitcnt vmcnt(0)
	s_branch .LBB0_264

; #define LAS __attribute__((address_space(3)))
; #define CONV_LOAD(it_) do { const int kb_ = (it_) / nblk, nb_ = (it_) % nblk; _Pragma("unroll") for (int i = 0; i < 8; ++i) { const int k_ = 64 * kb_ + 8 * i + (lane >> 3), n_ = 32 * nb_ + (lane & 7) * 4; \
;         nv[i] = (k_ < K && 32 * nb_ < N) ? *(const f32x4*)(W + (size_t)k_ * N + n_) : (f32x4){0.f, 0.f, 0.f, 0.f}; } } while (0)
; __device__ __forceinline__ void conv_mat(const float* W, int K, int N, bf16_t* WT, int Kp, int Np, LAS float* scr, int gw, int ngw, int lane) {
;     ...
;     for (int item = gw; item < nitems; item += ngw) {
;         const int kb = item / nblk, nb = item % nblk, k0 = 64 * kb, n0 = 32 * nb;
; #pragma unroll
;         for (int i = 0; i < 8; ++i) { const int kk = 8 * i + (lane >> 3), n4 = (lane & 7) * 4; LAS float* d = scr + kk * 33 + n4; d[0] = nv[i][0]; d[1] = nv[i][1]; d[2] = nv[i][2]; d[3] = nv[i][3]; }
;         if (item + ngw < nitems) CONV_LOAD(item + ngw);
.LBB0_264:
	v_add_u32_e32 v36, 0x420, v41
	s_waitcnt vmcnt(4)
	ds_write2_b32 v41, v8, v9 offset1:1
	ds_write2_b32 v41, v10, v11 offset0:2 offset1:3
	ds_write2_b32 v36, v4, v5 offset1:1
	v_add_u32_e32 v36, 0x428, v41
	ds_write2_b32 v36, v6, v7 offset1:1
	v_add_u32_e32 v36, 0x840, v41
	ds_write2_b32 v36, v16, v17 offset1:1
	v_add_u32_e32 v36, 0x848, v41
	ds_write2_b32 v36, v18, v19 offset1:1
	v_add_u32_e32 v36, 0xc60, v41
	ds_write2_b32 v36, v12, v13 offset1:1
	v_add_u32_e32 v36, 0xc68, v41
	ds_write2_b32 v36, v14, v15 offset1:1
	v_add_u32_e32 v36, 0x1080, v41
	ds_write2_b32 v36, v24, v25 offset1:1
	v_add_u32_e32 v36, 0x1088, v41
	ds_write2_b32 v36, v26, v27 offset1:1
	v_add_u32_e32 v36, 0x14a0, v41
	ds_write2_b32 v36, v20, v21 offset1:1
	v_add_u32_e32 v36, 0x14a8, v41
	ds_write2_b32 v36, v22, v23 offset1:1
	v_add_u32_e32 v36, 0x18c0, v41
	s_add_i32 s25, s24, s18
	ds_write2_b32 v36, v32, v33 offset1:1
	v_add_u32_e32 v36, 0x18c8, v41
	s_cmpk_gt_i32 s25, 0xff
	ds_write2_b32 v36, v34, v35 offset1:1
	v_add_u32_e32 v36, 0x1ce0, v41
	s_cselect_b64 s[12:13], -1, 0
	ds_write2_b32 v36, v28, v29 offset1:1
	v_add_u32_e32 v36, 0x1ce8, v41
	s_and_b64 vcc, exec, s[12:13]
	ds_write2_b32 v36, v30, v31 offset1:1
	s_cbranch_vccnz .LBB0_263
	s_ashr_i32 s14, s25, 31
	s_lshr_b32 s14, s14, 29
	s_add_i32 s14, s25, s14
	s_ashr_i32 s16, s14, 3
	s_and_b32 s14, s14, -8
	s_sub_i32 s14, s25, s14
	s_cmp_lt_i32 s14, 3
	v_lshl_or_b32 v29, s16, 6, v38
	s_cselect_b64 s[14:15], -1, 0
	v_add_u32_e32 v4, s23, v39
	s_lshl_b32 s16, s16, 8
	v_subrev_u32_e32 v4, s16, v4
	v_ashrrev_i32_e32 v5, 31, v4
	v_cmp_gt_i32_e32 vcc, s50, v29
	v_lshl_add_u64 v[36:37], v[4:5], 2, s[4:5]
	s_and_b64 s[26:27], s[14:15], vcc
	v_mov_b32_e32 v4, 0
	v_mov_b32_e32 v8, 0
	v_mov_b32_e32 v9, 0
	v_mov_b32_e32 v10, 0
	v_mov_b32_e32 v11, 0
	s_and_saveexec_b64 s[16:17], s[26:27]
	s_cbranch_execz .LBB0_267
	v_mad_i64_i32 v[6:7], s[26:27], v29, s31, v[36:37]
	global_load_dwordx4 v[8:11], v[6:7], off

; #define LAS __attribute__((address_space(3)))
; #define CONV_LOAD(it_) do { const int kb_ = (it_) / nblk, nb_ = (it_) % nblk; _Pragma("unroll") for (int i = 0; i < 8; ++i) { const int k_ = 64 * kb_ + 8 * i + (lane >> 3), n_ = 32 * nb_ + (lane & 7) * 4; \
;         nv[i] = (k_ < K && 32 * nb_ < N) ? *(const f32x4*)(W + (size_t)k_ * N + n_) : (f32x4){0.f, 0.f, 0.f, 0.f}; } } while (0)
; __device__ __forceinline__ void conv_mat(const float* W, int K, int N, bf16_t* WT, int Kp, int Np, LAS float* scr, int gw, int ngw, int lane) {
;     ...
;     if (gw < nitems) CONV_LOAD(gw);
;     for (int item = gw; item < nitems; item += ngw) {
;         const int kb = item / nblk, nb = item % nblk, k0 = 64 * kb, n0 = 32 * nb;
; #pragma unroll
;         for (int i = 0; i < 8; ++i) { const int kk = 8 * i + (lane >> 3), n4 = (lane & 7) * 4; LAS float* d = scr + kk * 33 + n4; d[0] = nv[i][0]; d[1] = nv[i][1]; d[2] = nv[i][2]; d[3] = nv[i][3]; }
;         if (item + ngw < nitems) CONV_LOAD(item + ngw);
;         asm volatile("s_waitcnt lgkmcnt(0)" ::: "memory");
;         const int c = lane & 7;
; #pragma unroll
;         for (int j = 0; j < 4; ++j) { const int n = (lane >> 3) + 8 * j; const LAS float* s = scr + (8 * c) * 33 + n;
.LBB0_298:
	s_or_b64 exec, exec, s[12:13]
	v_lshlrev_b32_e32 v0, 3, v40
	v_and_b32_e32 v0, 56, v0
	v_readlane_b32 s12, v235, 16
	v_lshlrev_b32_e32 v2, 1, v0
	v_readlane_b32 s13, v235, 17
	v_lshl_add_u32 v37, v36, 2, s20
	v_mul_u32_u24_e32 v39, 0x84, v0
	v_lshl_add_u64 v[0:1], s[12:13], 0, v[2:3]
	v_lshlrev_b32_e32 v2, 2, v38
	v_mul_u32_u24_e32 v41, 0x84, v38
	s_lshl_b32 s21, s19, 5
	s_lshl_b32 s22, s18, 5
	v_add3_u32 v2, s20, v39, v2
	v_or_b32_e32 v39, s21, v36
	v_add_u32_e32 v41, v37, v41
	s_mov_b32 s23, s22
	v_mov_b32_e32 v42, v38
	s_mov_b32 s24, s19
	s_waitcnt vmcnt(0)
	s_branch .LBB0_301

; #define LAS __attribute__((address_space(3)))
; #define CONV_LOAD(it_) do { const int kb_ = (it_) / nblk, nb_ = (it_) % nblk; _Pragma("unroll") for (int i = 0; i < 8; ++i) { const int k_ = 64 * kb_ + 8 * i + (lane >> 3), n_ = 32 * nb_ + (lane & 7) * 4; \
;         nv[i] = (k_ < K && 32 * nb_ < N) ? *(const f32x4*)(W + (size_t)k_ * N + n_) : (f32x4){0.f, 0.f, 0.f, 0.f}; } } while (0)
; __device__ __forceinline__ void conv_mat(const float* W, int K, int N, bf16_t* WT, int Kp, int Np, LAS float* scr, int gw, int ngw, int lane) {
;     ...
;     for (int item = gw; item < nitems; item += ngw) {
;         const int kb = item / nblk, nb = item % nblk, k0 = 64 * kb, n0 = 32 * nb;
; #pragma unroll
;         for (int i = 0; i < 8; ++i) { const int kk = 8 * i + (lane >> 3), n4 = (lane & 7) * 4; LAS float* d = scr + kk * 33 + n4; d[0] = nv[i][0]; d[1] = nv[i][1]; d[2] = nv[i][2]; d[3] = nv[i][3]; }
;         if (item + ngw < nitems) CONV_LOAD(item + ngw);
.LBB0_301:
	v_add_u32_e32 v36, 0x420, v41
	s_waitcnt vmcnt(4)
	ds_write2_b32 v41, v8, v9 offset1:1
	ds_write2_b32 v41, v10, v11 offset0:2 offset1:3
	ds_write2_b32 v36, v4, v5 offset1:1
	v_add_u32_e32 v36, 0x428, v41
	ds_write2_b32 v36, v6, v7 offset1:1
	v_add_u32_e32 v36, 0x840, v41
	ds_write2_b32 v36, v16, v17 offset1:1
	v_add_u32_e32 v36, 0x848, v41
	ds_write2_b32 v36, v18, v19 offset1:1
	v_add_u32_e32 v36, 0xc60, v41
	ds_write2_b32 v36, v12, v13 offset1:1
	v_add_u32_e32 v36, 0xc68, v41
	ds_write2_b32 v36, v14, v15 offset1:1
	v_add_u32_e32 v36, 0x1080, v41
	ds_write2_b32 v36, v24, v25 offset1:1
	v_add_u32_e32 v36, 0x1088, v41
	ds_write2_b32 v36, v26, v27 offset1:1
	v_add_u32_e32 v36, 0x14a0, v41
	ds_write2_b32 v36, v20, v21 offset1:1
	v_add_u32_e32 v36, 0x14a8, v41
	ds_write2_b32 v36, v22, v23 offset1:1
	v_add_u32_e32 v36, 0x18c0, v41
	s_add_i32 s25, s24, s18
	ds_write2_b32 v36, v32, v33 offset1:1
	v_add_u32_e32 v36, 0x18c8, v41
	s_cmpk_gt_i32 s25, 0xff
	ds_write2_b32 v36, v34, v35 offset1:1
	v_add_u32_e32 v36, 0x1ce0, v41
	s_cselect_b64 s[12:13], -1, 0
	ds_write2_b32 v36, v28, v29 offset1:1
	v_add_u32_e32 v36, 0x1ce8, v41
	s_and_b64 vcc, exec, s[12:13]
	ds_write2_b32 v36, v30, v31 offset1:1
	s_cbranch_vccnz .LBB0_300
	s_ashr_i32 s14, s25, 31
	s_lshr_b32 s14, s14, 29
	s_add_i32 s14, s25, s14
	s_ashr_i32 s16, s14, 3
	s_and_b32 s14, s14, -8
	s_sub_i32 s14, s25, s14
	s_cmp_lt_i32 s14, 3
	v_lshl_or_b32 v29, s16, 6, v38
	s_cselect_b64 s[14:15], -1, 0
	v_add_u32_e32 v4, s23, v39
	s_lshl_b32 s16, s16, 8
	v_subrev_u32_e32 v4, s16, v4
	v_ashrrev_i32_e32 v5, 31, v4
	v_cmp_gt_i32_e32 vcc, s50, v29
	v_lshl_add_u64 v[36:37], v[4:5], 2, s[10:11]
	s_and_b64 s[26:27], s[14:15], vcc
	v_mov_b32_e32 v4, 0
	v_mov_b32_e32 v8, 0
	v_mov_b32_e32 v9, 0
	v_mov_b32_e32 v10, 0
	v_mov_b32_e32 v11, 0
	s_and_saveexec_b64 s[16:17], s[26:27]
	s_cbranch_execz .LBB0_304
	v_mad_i64_i32 v[6:7], s[26:27], v29, s31, v[36:37]
	global_load_dwordx4 v[8:11], v[6:7], off

; #define LAS __attribute__((address_space(3)))
; #define CONV_LOAD(it_) do { const int kb_ = (it_) / nblk, nb_ = (it_) % nblk; _Pragma("unroll") for (int i = 0; i < 8; ++i) { const int k_ = 64 * kb_ + 8 * i + (lane >> 3), n_ = 32 * nb_ + (lane & 7) * 4; \
;         nv[i] = (k_ < K && 32 * nb_ < N) ? *(const f32x4*)(W + (size_t)k_ * N + n_) : (f32x4){0.f, 0.f, 0.f, 0.f}; } } while (0)
; __device__ __forceinline__ void conv_mat(const float* W, int K, int N, bf16_t* WT, int Kp, int Np, LAS float* scr, int gw, int ngw, int lane) {
;     ...
;     if (gw < nitems) CONV_LOAD(gw);
;     for (int item = gw; item < nitems; item += ngw) {
;         const int kb = item / nblk, nb = item % nblk, k0 = 64 * kb, n0 = 32 * nb;
; #pragma unroll
;         for (int i = 0; i < 8; ++i) { const int kk = 8 * i + (lane >> 3), n4 = (lane & 7) * 4; LAS float* d = scr + kk * 33 + n4; d[0] = nv[i][0]; d[1] = nv[i][1]; d[2] = nv[i][2]; d[3] = nv[i][3]; }
;         if (item + ngw < nitems) CONV_LOAD(item + ngw);
;         asm volatile("s_waitcnt lgkmcnt(0)" ::: "memory");
;         const int c = lane & 7;
; #pragma unroll
;         for (int j = 0; j < 4; ++j) { const int n = (lane >> 3) + 8 * j; const LAS float* s = scr + (8 * c) * 33 + n;
.LBB0_335:
	s_or_b64 exec, exec, s[14:15]
	v_lshlrev_b32_e32 v0, 3, v40
	v_and_b32_e32 v0, 56, v0
	v_readlane_b32 s14, v235, 18
	v_lshlrev_b32_e32 v2, 1, v0
	v_readlane_b32 s15, v235, 19
	v_mul_u32_u24_e32 v37, 0x84, v0
	v_lshl_add_u32 v36, v38, 2, s20
	v_lshl_add_u64 v[0:1], s[14:15], 0, v[2:3]
	v_lshlrev_b32_e32 v2, 2, v41
	v_add3_u32 v2, s20, v37, v2
	v_mul_u32_u24_e32 v37, 0x84, v41
	s_lshl_b32 s21, s19, 5
	s_lshl_b32 s22, s18, 5
	v_or_b32_e32 v42, s21, v38
	v_add_u32_e32 v43, v36, v37
	s_mov_b32 s23, s22
	v_mov_b32_e32 v44, v41
	s_mov_b32 s24, s19
	s_waitcnt vmcnt(0)
	s_branch .LBB0_338

; #define LAS __attribute__((address_space(3)))
; #define CONV_LOAD(it_) do { const int kb_ = (it_) / nblk, nb_ = (it_) % nblk; _Pragma("unroll") for (int i = 0; i < 8; ++i) { const int k_ = 64 * kb_ + 8 * i + (lane >> 3), n_ = 32 * nb_ + (lane & 7) * 4; \
;         nv[i] = (k_ < K && 32 * nb_ < N) ? *(const f32x4*)(W + (size_t)k_ * N + n_) : (f32x4){0.f, 0.f, 0.f, 0.f}; } } while (0)
; __device__ __forceinline__ void conv_mat(const float* W, int K, int N, bf16_t* WT, int Kp, int Np, LAS float* scr, int gw, int ngw, int lane) {
;     ...
;     for (int item = gw; item < nitems; item += ngw) {
;         const int kb = item / nblk, nb = item % nblk, k0 = 64 * kb, n0 = 32 * nb;
; #pragma unroll
;         for (int i = 0; i < 8; ++i) { const int kk = 8 * i + (lane >> 3), n4 = (lane & 7) * 4; LAS float* d = scr + kk * 33 + n4; d[0] = nv[i][0]; d[1] = nv[i][1]; d[2] = nv[i][2]; d[3] = nv[i][3]; }
;         if (item + ngw < nitems) CONV_LOAD(item + ngw);
.LBB0_338:
	v_add_u32_e32 v36, 0x420, v43
	s_waitcnt vmcnt(4)
	ds_write2_b32 v43, v8, v9 offset1:1
	ds_write2_b32 v43, v10, v11 offset0:2 offset1:3
	ds_write2_b32 v36, v4, v5 offset1:1
	v_add_u32_e32 v36, 0x428, v43
	ds_write2_b32 v36, v6, v7 offset1:1
	v_add_u32_e32 v36, 0x840, v43
	ds_write2_b32 v36, v16, v17 offset1:1
	v_add_u32_e32 v36, 0x848, v43
	ds_write2_b32 v36, v18, v19 offset1:1
	v_add_u32_e32 v36, 0xc60, v43
	ds_write2_b32 v36, v12, v13 offset1:1
	v_add_u32_e32 v36, 0xc68, v43
	ds_write2_b32 v36, v14, v15 offset1:1
	v_add_u32_e32 v36, 0x1080, v43
	ds_write2_b32 v36, v24, v25 offset1:1
	v_add_u32_e32 v36, 0x1088, v43
	ds_write2_b32 v36, v26, v27 offset1:1
	v_add_u32_e32 v36, 0x14a0, v43
	ds_write2_b32 v36, v20, v21 offset1:1
	v_add_u32_e32 v36, 0x14a8, v43
	ds_write2_b32 v36, v22, v23 offset1:1
	v_add_u32_e32 v36, 0x18c0, v43
	s_add_i32 s25, s24, s18
	ds_write2_b32 v36, v32, v33 offset1:1
	v_add_u32_e32 v36, 0x18c8, v43
	s_cmpk_gt_i32 s25, 0xff
	ds_write2_b32 v36, v34, v35 offset1:1
	v_add_u32_e32 v36, 0x1ce0, v43
	s_cselect_b64 s[14:15], -1, 0
	ds_write2_b32 v36, v28, v29 offset1:1
	v_add_u32_e32 v36, 0x1ce8, v43
	s_and_b64 vcc, exec, s[14:15]
	ds_write2_b32 v36, v30, v31 offset1:1
	s_cbranch_vccnz .LBB0_337
	s_ashr_i32 s16, s25, 31
	s_lshr_b32 s16, s16, 29
	s_add_i32 s16, s25, s16
	s_ashr_i32 s16, s16, 3
	v_lshl_or_b32 v30, s16, 6, v41
	v_add_u32_e32 v4, s23, v42
	s_lshl_b32 s16, s16, 8
	v_subrev_u32_e32 v4, s16, v4
	v_ashrrev_i32_e32 v5, 31, v4
	v_lshl_add_u64 v[36:37], v[4:5], 2, s[12:13]
	v_cmp_gt_i32_e32 vcc, s50, v30
	v_mov_b32_e32 v4, 0
	v_mov_b32_e32 v8, 0
	v_mov_b32_e32 v9, 0
	v_mov_b32_e32 v10, 0
	v_mov_b32_e32 v11, 0
	s_and_saveexec_b64 s[16:17], vcc
	s_cbranch_execz .LBB0_341
	v_ashrrev_i32_e32 v31, 31, v30
	v_lshlrev_b64 v[6:7], 10, v[30:31]
	v_lshl_add_u64 v[6:7], v[36:37], 0, v[6:7]
	global_load_dwordx4 v[8:11], v[6:7], off

; #define LAS __attribute__((address_space(3)))
; #define CONV_LOAD(it_) do { const int kb_ = (it_) / nblk, nb_ = (it_) % nblk; _Pragma("unroll") for (int i = 0; i < 8; ++i) { const int k_ = 64 * kb_ + 8 * i + (lane >> 3), n_ = 32 * nb_ + (lane & 7) * 4; \
;         nv[i] = (k_ < K && 32 * nb_ < N) ? *(const f32x4*)(W + (size_t)k_ * N + n_) : (f32x4){0.f, 0.f, 0.f, 0.f}; } } while (0)
; __device__ __forceinline__ void conv_mat(const float* W, int K, int N, bf16_t* WT, int Kp, int Np, LAS float* scr, int gw, int ngw, int lane) {
;     ...
;     if (gw < nitems) CONV_LOAD(gw);
;     for (int item = gw; item < nitems; item += ngw) {
;         const int kb = item / nblk, nb = item % nblk, k0 = 64 * kb, n0 = 32 * nb;
; #pragma unroll
;         for (int i = 0; i < 8; ++i) { const int kk = 8 * i + (lane >> 3), n4 = (lane & 7) * 4; LAS float* d = scr + kk * 33 + n4; d[0] = nv[i][0]; d[1] = nv[i][1]; d[2] = nv[i][2]; d[3] = nv[i][3]; }
;         if (item + ngw < nitems) CONV_LOAD(item + ngw);
;         asm volatile("s_waitcnt lgkmcnt(0)" ::: "memory");
;         const int c = lane & 7;
; #pragma unroll
;         for (int j = 0; j < 4; ++j) { const int n = (lane >> 3) + 8 * j; const LAS float* s = scr + (8 * c) * 33 + n;
.LBB0_372:
	s_or_b64 exec, exec, s[14:15]
	v_lshlrev_b32_e32 v0, 3, v40
	v_and_b32_e32 v0, 56, v0
	v_readlane_b32 s14, v235, 20
	v_lshlrev_b32_e32 v2, 1, v0
	v_readlane_b32 s15, v235, 21
	v_mul_u32_u24_e32 v37, 0x84, v0
	v_lshl_add_u32 v36, v38, 2, s20
	v_lshl_add_u64 v[0:1], s[14:15], 0, v[2:3]
	v_lshlrev_b32_e32 v2, 2, v41
	v_add3_u32 v2, s20, v37, v2
	v_mul_u32_u24_e32 v37, 0x84, v41
	s_lshl_b32 s21, s19, 5
	s_lshl_b32 s22, s18, 5
	v_or_b32_e32 v42, s21, v38
	v_add_u32_e32 v43, v36, v37
	s_mov_b32 s23, s22
	v_mov_b32_e32 v44, v41
	s_mov_b32 s24, s19
	s_waitcnt vmcnt(0)
	s_branch .LBB0_375

; #define LAS __attribute__((address_space(3)))
; #define CONV_LOAD(it_) do { const int kb_ = (it_) / nblk, nb_ = (it_) % nblk; _Pragma("unroll") for (int i = 0; i < 8; ++i) { const int k_ = 64 * kb_ + 8 * i + (lane >> 3), n_ = 32 * nb_ + (lane & 7) * 4; \
;         nv[i] = (k_ < K && 32 * nb_ < N) ? *(const f32x4*)(W + (size_t)k_ * N + n_) : (f32x4){0.f, 0.f, 0.f, 0.f}; } } while (0)
; __device__ __forceinline__ void conv_mat(const float* W, int K, int N, bf16_t* WT, int Kp, int Np, LAS float* scr, int gw, int ngw, int lane) {
;     ...
;     for (int item = gw; item < nitems; item += ngw) {
;         const int kb = item / nblk, nb = item % nblk, k0 = 64 * kb, n0 = 32 * nb;
; #pragma unroll
;         for (int i = 0; i < 8; ++i) { const int kk = 8 * i + (lane >> 3), n4 = (lane & 7) * 4; LAS float* d = scr + kk * 33 + n4; d[0] = nv[i][0]; d[1] = nv[i][1]; d[2] = nv[i][2]; d[3] = nv[i][3]; }
;         if (item + ngw < nitems) CONV_LOAD(item + ngw);
.LBB0_375:
	v_add_u32_e32 v36, 0x420, v43
	s_waitcnt vmcnt(4)
	ds_write2_b32 v43, v8, v9 offset1:1
	ds_write2_b32 v43, v10, v11 offset0:2 offset1:3
	ds_write2_b32 v36, v4, v5 offset1:1
	v_add_u32_e32 v36, 0x428, v43
	ds_write2_b32 v36, v6, v7 offset1:1
	v_add_u32_e32 v36, 0x840, v43
	ds_write2_b32 v36, v16, v17 offset1:1
	v_add_u32_e32 v36, 0x848, v43
	ds_write2_b32 v36, v18, v19 offset1:1
	v_add_u32_e32 v36, 0xc60, v43
	ds_write2_b32 v36, v12, v13 offset1:1
	v_add_u32_e32 v36, 0xc68, v43
	ds_write2_b32 v36, v14, v15 offset1:1
	v_add_u32_e32 v36, 0x1080, v43
	ds_write2_b32 v36, v24, v25 offset1:1
	v_add_u32_e32 v36, 0x1088, v43
	ds_write2_b32 v36, v26, v27 offset1:1
	v_add_u32_e32 v36, 0x14a0, v43
	ds_write2_b32 v36, v20, v21 offset1:1
	v_add_u32_e32 v36, 0x14a8, v43
	ds_write2_b32 v36, v22, v23 offset1:1
	v_add_u32_e32 v36, 0x18c0, v43
	s_add_i32 s25, s24, s18
	ds_write2_b32 v36, v32, v33 offset1:1
	v_add_u32_e32 v36, 0x18c8, v43
	s_cmpk_gt_i32 s25, 0xff
	ds_write2_b32 v36, v34, v35 offset1:1
	v_add_u32_e32 v36, 0x1ce0, v43
	s_cselect_b64 s[14:15], -1, 0
	ds_write2_b32 v36, v28, v29 offset1:1
	v_add_u32_e32 v36, 0x1ce8, v43
	s_and_b64 vcc, exec, s[14:15]
	ds_write2_b32 v36, v30, v31 offset1:1
	s_cbranch_vccnz .LBB0_374
	s_ashr_i32 s16, s25, 31
	s_lshr_b32 s16, s16, 26
	s_add_i32 s16, s25, s16
	s_and_b32 s17, s16, 0xffffffc0
	s_lshl_b32 s16, s16, 5
	v_add_u32_e32 v4, s23, v42
	s_and_b32 s16, s16, 0xfffff800
	v_subrev_u32_e32 v4, s16, v4
	v_or_b32_e32 v30, s17, v41
	v_ashrrev_i32_e32 v5, 31, v4
	v_lshl_add_u64 v[36:37], v[4:5], 2, s[12:13]
	v_cmp_gt_i32_e32 vcc, s31, v30
	v_mov_b32_e32 v4, 0
	v_mov_b32_e32 v8, 0
	v_mov_b32_e32 v9, 0
	v_mov_b32_e32 v10, 0
	v_mov_b32_e32 v11, 0
	s_and_saveexec_b64 s[16:17], vcc
	s_cbranch_execz .LBB0_378
	v_ashrrev_i32_e32 v31, 31, v30
	v_lshlrev_b64 v[6:7], 13, v[30:31]
	v_lshl_add_u64 v[6:7], v[36:37], 0, v[6:7]
	global_load_dwordx4 v[8:11], v[6:7], off

; #define LAS __attribute__((address_space(3)))
; #define CONV_LOAD(it_) do { const int kb_ = (it_) / nblk, nb_ = (it_) % nblk; _Pragma("unroll") for (int i = 0; i < 8; ++i) { const int k_ = 64 * kb_ + 8 * i + (lane >> 3), n_ = 32 * nb_ + (lane & 7) * 4; \
;         nv[i] = (k_ < K && 32 * nb_ < N) ? *(const f32x4*)(W + (size_t)k_ * N + n_) : (f32x4){0.f, 0.f, 0.f, 0.f}; } } while (0)
; __device__ __forceinline__ void conv_mat(const float* W, int K, int N, bf16_t* WT, int Kp, int Np, LAS float* scr, int gw, int ngw, int lane) {
;     ...
;     if (gw < nitems) CONV_LOAD(gw);
;     for (int item = gw; item < nitems; item += ngw) {
;         const int kb = item / nblk, nb = item % nblk, k0 = 64 * kb, n0 = 32 * nb;
; #pragma unroll
;         for (int i = 0; i < 8; ++i) { const int kk = 8 * i + (lane >> 3), n4 = (lane & 7) * 4; LAS float* d = scr + kk * 33 + n4; d[0] = nv[i][0]; d[1] = nv[i][1]; d[2] = nv[i][2]; d[3] = nv[i][3]; }
;         if (item + ngw < nitems) CONV_LOAD(item + ngw);
;         asm volatile("s_waitcnt lgkmcnt(0)" ::: "memory");
;         const int c = lane & 7;
; #pragma unroll
;         for (int j = 0; j < 4; ++j) { const int n = (lane >> 3) + 8 * j; const LAS float* s = scr + (8 * c) * 33 + n;
.LBB0_409:
	s_or_b64 exec, exec, s[12:13]
	v_lshlrev_b32_e32 v0, 3, v40
	v_and_b32_e32 v0, 56, v0
	v_readlane_b32 s12, v235, 22
	v_lshlrev_b32_e32 v2, 1, v0
	v_readlane_b32 s13, v235, 23
	v_mul_u32_u24_e32 v37, 0x84, v0
	v_lshl_add_u32 v36, v38, 2, s20
	v_lshl_add_u64 v[0:1], s[12:13], 0, v[2:3]
	v_lshlrev_b32_e32 v2, 2, v41
	v_add3_u32 v2, s20, v37, v2
	v_mul_u32_u24_e32 v37, 0x84, v41
	s_lshl_b32 s16, s19, 5
	s_lshl_b32 s17, s18, 5
	v_or_b32_e32 v42, s16, v38
	v_add_u32_e32 v43, v36, v37
	s_mov_b32 s21, s17
	v_mov_b32_e32 v44, v41
	s_mov_b32 s22, s19
	s_waitcnt vmcnt(0)
	s_branch .LBB0_412

; #define LAS __attribute__((address_space(3)))
; #define CONV_LOAD(it_) do { const int kb_ = (it_) / nblk, nb_ = (it_) % nblk; _Pragma("unroll") for (int i = 0; i < 8; ++i) { const int k_ = 64 * kb_ + 8 * i + (lane >> 3), n_ = 32 * nb_ + (lane & 7) * 4; \
;         nv[i] = (k_ < K && 32 * nb_ < N) ? *(const f32x4*)(W + (size_t)k_ * N + n_) : (f32x4){0.f, 0.f, 0.f, 0.f}; } } while (0)
; __device__ __forceinline__ void conv_mat(const float* W, int K, int N, bf16_t* WT, int Kp, int Np, LAS float* scr, int gw, int ngw, int lane) {
;     ...
;     for (int item = gw; item < nitems; item += ngw) {
;         const int kb = item / nblk, nb = item % nblk, k0 = 64 * kb, n0 = 32 * nb;
; #pragma unroll
;         for (int i = 0; i < 8; ++i) { const int kk = 8 * i + (lane >> 3), n4 = (lane & 7) * 4; LAS float* d = scr + kk * 33 + n4; d[0] = nv[i][0]; d[1] = nv[i][1]; d[2] = nv[i][2]; d[3] = nv[i][3]; }
;         if (item + ngw < nitems) CONV_LOAD(item + ngw);
.LBB0_412:
	v_add_u32_e32 v36, 0x420, v43
	s_waitcnt vmcnt(4)
	ds_write2_b32 v43, v8, v9 offset1:1
	ds_write2_b32 v43, v10, v11 offset0:2 offset1:3
	ds_write2_b32 v36, v4, v5 offset1:1
	v_add_u32_e32 v36, 0x428, v43
	ds_write2_b32 v36, v6, v7 offset1:1
	v_add_u32_e32 v36, 0x840, v43
	ds_write2_b32 v36, v16, v17 offset1:1
	v_add_u32_e32 v36, 0x848, v43
	ds_write2_b32 v36, v18, v19 offset1:1
	v_add_u32_e32 v36, 0xc60, v43
	ds_write2_b32 v36, v12, v13 offset1:1
	v_add_u32_e32 v36, 0xc68, v43
	ds_write2_b32 v36, v14, v15 offset1:1
	v_add_u32_e32 v36, 0x1080, v43
	ds_write2_b32 v36, v24, v25 offset1:1
	v_add_u32_e32 v36, 0x1088, v43
	ds_write2_b32 v36, v26, v27 offset1:1
	v_add_u32_e32 v36, 0x14a0, v43
	ds_write2_b32 v36, v20, v21 offset1:1
	v_add_u32_e32 v36, 0x14a8, v43
	ds_write2_b32 v36, v22, v23 offset1:1
	v_add_u32_e32 v36, 0x18c0, v43
	s_add_i32 s23, s22, s18
	ds_write2_b32 v36, v32, v33 offset1:1
	v_add_u32_e32 v36, 0x18c8, v43
	s_cmpk_gt_i32 s23, 0xff
	ds_write2_b32 v36, v34, v35 offset1:1
	v_add_u32_e32 v36, 0x1ce0, v43
	s_cselect_b64 s[12:13], -1, 0
	ds_write2_b32 v36, v28, v29 offset1:1
	v_add_u32_e32 v36, 0x1ce8, v43
	s_and_b64 vcc, exec, s[12:13]
	ds_write2_b32 v36, v30, v31 offset1:1
	s_cbranch_vccnz .LBB0_411
	s_ashr_i32 s14, s23, 31
	s_lshr_b32 s14, s14, 26
	s_add_i32 s14, s23, s14
	s_and_b32 s15, s14, 0xffffffc0
	s_lshl_b32 s14, s14, 5
	v_add_u32_e32 v4, s21, v42
	s_and_b32 s14, s14, 0xfffff800
	v_subrev_u32_e32 v4, s14, v4
	v_or_b32_e32 v30, s15, v41
	v_ashrrev_i32_e32 v5, 31, v4
	v_lshl_add_u64 v[36:37], v[4:5], 2, s[2:3]
	v_cmp_gt_i32_e32 vcc, s31, v30
	v_mov_b32_e32 v4, 0
	v_mov_b32_e32 v8, 0
	v_mov_b32_e32 v9, 0
	v_mov_b32_e32 v10, 0
	v_mov_b32_e32 v11, 0
	s_and_saveexec_b64 s[14:15], vcc
	s_cbranch_execz .LBB0_415
	v_ashrrev_i32_e32 v31, 31, v30
	v_lshlrev_b64 v[6:7], 13, v[30:31]
	v_lshl_add_u64 v[6:7], v[36:37], 0, v[6:7]
	global_load_dwordx4 v[8:11], v[6:7], off

; #define LAS __attribute__((address_space(3)))
; #define CONV_LOAD(it_) do { const int kb_ = (it_) / nblk, nb_ = (it_) % nblk; _Pragma("unroll") for (int i = 0; i < 8; ++i) { const int k_ = 64 * kb_ + 8 * i + (lane >> 3), n_ = 32 * nb_ + (lane & 7) * 4; \
;         nv[i] = (k_ < K && 32 * nb_ < N) ? *(const f32x4*)(W + (size_t)k_ * N + n_) : (f32x4){0.f, 0.f, 0.f, 0.f}; } } while (0)
; __device__ __forceinline__ void conv_mat(const float* W, int K, int N, bf16_t* WT, int Kp, int Np, LAS float* scr, int gw, int ngw, int lane) {
;     ...
;     if (gw < nitems) CONV_LOAD(gw);
;     for (int item = gw; item < nitems; item += ngw) {
;         const int kb = item / nblk, nb = item % nblk, k0 = 64 * kb, n0 = 32 * nb;
; #pragma unroll
;         for (int i = 0; i < 8; ++i) { const int kk = 8 * i + (lane >> 3), n4 = (lane & 7) * 4; LAS float* d = scr + kk * 33 + n4; d[0] = nv[i][0]; d[1] = nv[i][1]; d[2] = nv[i][2]; d[3] = nv[i][3]; }
;         if (item + ngw < nitems) CONV_LOAD(item + ngw);
;         asm volatile("s_waitcnt lgkmcnt(0)" ::: "memory");
;         const int c = lane & 7;
; #pragma unroll
;         for (int j = 0; j < 4; ++j) { const int n = (lane >> 3) + 8 * j; const LAS float* s = scr + (8 * c) * 33 + n;
.LBB0_446:
	s_or_b64 exec, exec, s[10:11]
	v_lshlrev_b32_e32 v0, 3, v40
	v_and_b32_e32 v0, 56, v0
	v_readlane_b32 s10, v235, 24
	v_lshlrev_b32_e32 v2, 1, v0
	v_readlane_b32 s11, v235, 25
	v_mul_u32_u24_e32 v37, 0x84, v0
	v_lshl_add_u32 v36, v38, 2, s20
	v_lshl_add_u64 v[0:1], s[10:11], 0, v[2:3]
	v_lshlrev_b32_e32 v2, 2, v41
	v_add3_u32 v2, s20, v37, v2
	v_mul_u32_u24_e32 v37, 0x84, v41
	s_lshl_b32 s14, s19, 5
	s_lshl_b32 s15, s18, 5
	v_or_b32_e32 v42, s14, v38
	v_add_u32_e32 v43, v36, v37
	s_mov_b32 s16, s15
	v_mov_b32_e32 v44, v41
	s_mov_b32 s17, s19
	s_waitcnt vmcnt(0)
	s_branch .LBB0_449

; #define LAS __attribute__((address_space(3)))
; #define CONV_LOAD(it_) do { const int kb_ = (it_) / nblk, nb_ = (it_) % nblk; _Pragma("unroll") for (int i = 0; i < 8; ++i) { const int k_ = 64 * kb_ + 8 * i + (lane >> 3), n_ = 32 * nb_ + (lane & 7) * 4; \
;         nv[i] = (k_ < K && 32 * nb_ < N) ? *(const f32x4*)(W + (size_t)k_ * N + n_) : (f32x4){0.f, 0.f, 0.f, 0.f}; } } while (0)
; __device__ __forceinline__ void conv_mat(const float* W, int K, int N, bf16_t* WT, int Kp, int Np, LAS float* scr, int gw, int ngw, int lane) {
;     ...
;     for (int item = gw; item < nitems; item += ngw) {
;         const int kb = item / nblk, nb = item % nblk, k0 = 64 * kb, n0 = 32 * nb;
; #pragma unroll
;         for (int i = 0; i < 8; ++i) { const int kk = 8 * i + (lane >> 3), n4 = (lane & 7) * 4; LAS float* d = scr + kk * 33 + n4; d[0] = nv[i][0]; d[1] = nv[i][1]; d[2] = nv[i][2]; d[3] = nv[i][3]; }
;         if (item + ngw < nitems) CONV_LOAD(item + ngw);
.LBB0_449:
	v_add_u32_e32 v36, 0x420, v43
	s_waitcnt vmcnt(4)
	ds_write2_b32 v43, v8, v9 offset1:1
	ds_write2_b32 v43, v10, v11 offset0:2 offset1:3
	ds_write2_b32 v36, v4, v5 offset1:1
	v_add_u32_e32 v36, 0x428, v43
	ds_write2_b32 v36, v6, v7 offset1:1
	v_add_u32_e32 v36, 0x840, v43
	ds_write2_b32 v36, v16, v17 offset1:1
	v_add_u32_e32 v36, 0x848, v43
	ds_write2_b32 v36, v18, v19 offset1:1
	v_add_u32_e32 v36, 0xc60, v43
	ds_write2_b32 v36, v12, v13 offset1:1
	v_add_u32_e32 v36, 0xc68, v43
	ds_write2_b32 v36, v14, v15 offset1:1
	v_add_u32_e32 v36, 0x1080, v43
	ds_write2_b32 v36, v24, v25 offset1:1
	v_add_u32_e32 v36, 0x1088, v43
	ds_write2_b32 v36, v26, v27 offset1:1
	v_add_u32_e32 v36, 0x14a0, v43
	ds_write2_b32 v36, v20, v21 offset1:1
	v_add_u32_e32 v36, 0x14a8, v43
	ds_write2_b32 v36, v22, v23 offset1:1
	v_add_u32_e32 v36, 0x18c0, v43
	s_add_i32 s21, s17, s18
	ds_write2_b32 v36, v32, v33 offset1:1
	v_add_u32_e32 v36, 0x18c8, v43
	s_cmpk_gt_i32 s21, 0xff
	ds_write2_b32 v36, v34, v35 offset1:1
	v_add_u32_e32 v36, 0x1ce0, v43
	s_cselect_b64 s[10:11], -1, 0
	ds_write2_b32 v36, v28, v29 offset1:1
	v_add_u32_e32 v36, 0x1ce8, v43
	s_and_b64 vcc, exec, s[10:11]
	ds_write2_b32 v36, v30, v31 offset1:1
	s_cbranch_vccnz .LBB0_448
	s_ashr_i32 s12, s21, 31
	s_lshr_b32 s12, s12, 26
	s_add_i32 s12, s21, s12
	s_and_b32 s13, s12, 0xffffffc0
	s_lshl_b32 s12, s12, 5
	v_add_u32_e32 v4, s16, v42
	s_and_b32 s12, s12, 0xfffff800
	v_subrev_u32_e32 v4, s12, v4
	v_or_b32_e32 v30, s13, v41
	v_ashrrev_i32_e32 v5, 31, v4
	v_lshl_add_u64 v[36:37], v[4:5], 2, s[2:3]
	v_cmp_gt_i32_e32 vcc, s30, v30
	v_mov_b32_e32 v4, 0
	v_mov_b32_e32 v8, 0
	v_mov_b32_e32 v9, 0
	v_mov_b32_e32 v10, 0
	v_mov_b32_e32 v11, 0
	s_and_saveexec_b64 s[12:13], vcc
	s_cbranch_execz .LBB0_452
	v_ashrrev_i32_e32 v31, 31, v30
	v_lshlrev_b64 v[6:7], 13, v[30:31]
	v_lshl_add_u64 v[6:7], v[36:37], 0, v[6:7]
	global_load_dwordx4 v[8:11], v[6:7], off

; #define LAS __attribute__((address_space(3)))
; #define CONV_LOAD(it_) do { const int kb_ = (it_) / nblk, nb_ = (it_) % nblk; _Pragma("unroll") for (int i = 0; i < 8; ++i) { const int k_ = 64 * kb_ + 8 * i + (lane >> 3), n_ = 32 * nb_ + (lane & 7) * 4; \
;         nv[i] = (k_ < K && 32 * nb_ < N) ? *(const f32x4*)(W + (size_t)k_ * N + n_) : (f32x4){0.f, 0.f, 0.f, 0.f}; } } while (0)
; __device__ __forceinline__ void conv_mat(const float* W, int K, int N, bf16_t* WT, int Kp, int Np, LAS float* scr, int gw, int ngw, int lane) {
;     ...
;     if (gw < nitems) CONV_LOAD(gw);
;     for (int item = gw; item < nitems; item += ngw) {
;         const int kb = item / nblk, nb = item % nblk, k0 = 64 * kb, n0 = 32 * nb;
; #pragma unroll
;         for (int i = 0; i < 8; ++i) { const int kk = 8 * i + (lane >> 3), n4 = (lane & 7) * 4; LAS float* d = scr + kk * 33 + n4; d[0] = nv[i][0]; d[1] = nv[i][1]; d[2] = nv[i][2]; d[3] = nv[i][3]; }
;         if (item + ngw < nitems) CONV_LOAD(item + ngw);
;         asm volatile("s_waitcnt lgkmcnt(0)" ::: "memory");
;         const int c = lane & 7;
; #pragma unroll
;         for (int j = 0; j < 4; ++j) { const int n = (lane >> 3) + 8 * j; const LAS float* s = scr + (8 * c) * 33 + n;
.LBB0_484:
	s_or_b64 exec, exec, s[10:11]
	v_lshlrev_b32_e32 v0, 3, v40
	v_and_b32_e32 v0, 56, v0
	v_readlane_b32 s10, v235, 26
	v_lshlrev_b32_e32 v2, 1, v0
	v_readlane_b32 s11, v235, 27
	v_mul_u32_u24_e32 v37, 0x84, v0
	v_lshl_add_u32 v36, v38, 2, s20
	v_lshl_add_u64 v[0:1], s[10:11], 0, v[2:3]
	v_lshlrev_b32_e32 v2, 2, v41
	v_add3_u32 v2, s20, v37, v2
	v_mul_u32_u24_e32 v37, 0x84, v41
	s_lshl_b32 s21, s19, 5
	s_lshl_b32 s22, s18, 5
	v_or_b32_e32 v42, s21, v38
	v_add_u32_e32 v43, v36, v37
	s_mov_b32 s23, s22
	v_mov_b32_e32 v44, v41
	s_mov_b32 s24, s19
	s_waitcnt vmcnt(0)
	s_branch .LBB0_487

; #define LAS __attribute__((address_space(3)))
; #define CONV_LOAD(it_) do { const int kb_ = (it_) / nblk, nb_ = (it_) % nblk; _Pragma("unroll") for (int i = 0; i < 8; ++i) { const int k_ = 64 * kb_ + 8 * i + (lane >> 3), n_ = 32 * nb_ + (lane & 7) * 4; \
;         nv[i] = (k_ < K && 32 * nb_ < N) ? *(const f32x4*)(W + (size_t)k_ * N + n_) : (f32x4){0.f, 0.f, 0.f, 0.f}; } } while (0)
; __device__ __forceinline__ void conv_mat(const float* W, int K, int N, bf16_t* WT, int Kp, int Np, LAS float* scr, int gw, int ngw, int lane) {
;     ...
;     for (int item = gw; item < nitems; item += ngw) {
;         const int kb = item / nblk, nb = item % nblk, k0 = 64 * kb, n0 = 32 * nb;
; #pragma unroll
;         for (int i = 0; i < 8; ++i) { const int kk = 8 * i + (lane >> 3), n4 = (lane & 7) * 4; LAS float* d = scr + kk * 33 + n4; d[0] = nv[i][0]; d[1] = nv[i][1]; d[2] = nv[i][2]; d[3] = nv[i][3]; }
;         if (item + ngw < nitems) CONV_LOAD(item + ngw);
.LBB0_487:
	v_add_u32_e32 v36, 0x420, v43
	s_waitcnt vmcnt(4)
	ds_write2_b32 v43, v8, v9 offset1:1
	ds_write2_b32 v43, v10, v11 offset0:2 offset1:3
	ds_write2_b32 v36, v4, v5 offset1:1
	v_add_u32_e32 v36, 0x428, v43
	ds_write2_b32 v36, v6, v7 offset1:1
	v_add_u32_e32 v36, 0x840, v43
	ds_write2_b32 v36, v16, v17 offset1:1
	v_add_u32_e32 v36, 0x848, v43
	ds_write2_b32 v36, v18, v19 offset1:1
	v_add_u32_e32 v36, 0xc60, v43
	ds_write2_b32 v36, v12, v13 offset1:1
	v_add_u32_e32 v36, 0xc68, v43
	ds_write2_b32 v36, v14, v15 offset1:1
	v_add_u32_e32 v36, 0x1080, v43
	ds_write2_b32 v36, v24, v25 offset1:1
	v_add_u32_e32 v36, 0x1088, v43
	ds_write2_b32 v36, v26, v27 offset1:1
	v_add_u32_e32 v36, 0x14a0, v43
	ds_write2_b32 v36, v20, v21 offset1:1
	v_add_u32_e32 v36, 0x14a8, v43
	ds_write2_b32 v36, v22, v23 offset1:1
	v_add_u32_e32 v36, 0x18c0, v43
	s_add_i32 s25, s24, s18
	ds_write2_b32 v36, v32, v33 offset1:1
	v_add_u32_e32 v36, 0x18c8, v43
	s_cmpk_gt_i32 s25, 0xff
	ds_write2_b32 v36, v34, v35 offset1:1
	v_add_u32_e32 v36, 0x1ce0, v43
	s_cselect_b64 s[10:11], -1, 0
	ds_write2_b32 v36, v28, v29 offset1:1
	v_add_u32_e32 v36, 0x1ce8, v43
	s_and_b64 vcc, exec, s[10:11]
	ds_write2_b32 v36, v30, v31 offset1:1
	s_cbranch_vccnz .LBB0_486
	s_ashr_i32 s12, s25, 31
	s_lshr_b32 s12, s12, 29
	s_add_i32 s12, s25, s12
	s_ashr_i32 s14, s12, 3
	s_and_b32 s12, s12, -8
	s_sub_i32 s12, s25, s12
	s_cmp_lt_i32 s12, 2
	v_lshl_or_b32 v30, s14, 6, v41
	s_cselect_b64 s[12:13], -1, 0
	v_add_u32_e32 v4, s23, v42
	s_lshl_b32 s14, s14, 8
	v_subrev_u32_e32 v4, s14, v4
	v_ashrrev_i32_e32 v5, 31, v4
	v_cmp_gt_i32_e32 vcc, s50, v30
	v_lshl_add_u64 v[36:37], v[4:5], 2, s[2:3]
	s_and_b64 s[26:27], s[12:13], vcc
	v_mov_b32_e32 v4, 0
	v_mov_b32_e32 v8, 0
	v_mov_b32_e32 v9, 0
	v_mov_b32_e32 v10, 0
	v_mov_b32_e32 v11, 0
	s_and_saveexec_b64 s[14:15], s[26:27]
	s_cbranch_execz .LBB0_490
	v_ashrrev_i32_e32 v31, 31, v30
	v_lshlrev_b64 v[6:7], 8, v[30:31]
	v_lshl_add_u64 v[6:7], v[36:37], 0, v[6:7]
	global_load_dwordx4 v[8:11], v[6:7], off

; #define LAS __attribute__((address_space(3)))
; #define CONV_LOAD(it_) do { const int kb_ = (it_) / nblk, nb_ = (it_) % nblk; _Pragma("unroll") for (int i = 0; i < 8; ++i) { const int k_ = 64 * kb_ + 8 * i + (lane >> 3), n_ = 32 * nb_ + (lane & 7) * 4; \
;         nv[i] = (k_ < K && 32 * nb_ < N) ? *(const f32x4*)(W + (size_t)k_ * N + n_) : (f32x4){0.f, 0.f, 0.f, 0.f}; } } while (0)
; __device__ __forceinline__ void conv_mat(const float* W, int K, int N, bf16_t* WT, int Kp, int Np, LAS float* scr, int gw, int ngw, int lane) {
;     ...
;     if (gw < nitems) CONV_LOAD(gw);
;     for (int item = gw; item < nitems; item += ngw) {
;         const int kb = item / nblk, nb = item % nblk, k0 = 64 * kb, n0 = 32 * nb;
; #pragma unroll
;         for (int i = 0; i < 8; ++i) { const int kk = 8 * i + (lane >> 3), n4 = (lane & 7) * 4; LAS float* d = scr + kk * 33 + n4; d[0] = nv[i][0]; d[1] = nv[i][1]; d[2] = nv[i][2]; d[3] = nv[i][3]; }
;         if (item + ngw < nitems) CONV_LOAD(item + ngw);
;         asm volatile("s_waitcnt lgkmcnt(0)" ::: "memory");
;         const int c = lane & 7;
; #pragma unroll
;         for (int j = 0; j < 4; ++j) { const int n = (lane >> 3) + 8 * j; const LAS float* s = scr + (8 * c) * 33 + n;
.LBB0_521:
	s_or_b64 exec, exec, s[4:5]
	v_lshlrev_b32_e32 v0, 3, v40
	v_and_b32_e32 v0, 56, v0
	v_readlane_b32 s4, v235, 28
	v_lshlrev_b32_e32 v2, 1, v0
	v_readlane_b32 s5, v235, 29
	v_mul_u32_u24_e32 v37, 0x84, v0
	v_lshl_add_u32 v36, v38, 2, s20
	v_lshl_add_u64 v[0:1], s[4:5], 0, v[2:3]
	v_lshlrev_b32_e32 v2, 2, v41
	v_add3_u32 v2, s20, v37, v2
	v_mul_u32_u24_e32 v37, 0x84, v41
	s_lshl_b32 s12, s19, 5
	s_lshl_b32 s13, s18, 5
	v_or_b32_e32 v42, s12, v38
	v_add_u32_e32 v43, v36, v37
	s_mov_b32 s14, s13
	v_mov_b32_e32 v44, v41
	s_mov_b32 s15, s19
	s_waitcnt vmcnt(0)
	s_branch .LBB0_524

; #define LAS __attribute__((address_space(3)))
; __device__ __forceinline__ unsigned pk2(float lo, float hi) { f32x2c v = {lo, hi}; return __builtin_bit_cast(unsigned, __builtin_convertvector(v, bf16x2c)); }
; #define CONV_LOAD(it_) do { const int kb_ = (it_) / nblk, nb_ = (it_) % nblk; _Pragma("unroll") for (int i = 0; i < 8; ++i) { const int k_ = 64 * kb_ + 8 * i + (lane >> 3), n_ = 32 * nb_ + (lane & 7) * 4; \
;         nv[i] = (k_ < K && 32 * nb_ < N) ? *(const f32x4*)(W + (size_t)k_ * N + n_) : (f32x4){0.f, 0.f, 0.f, 0.f}; } } while (0)
; __device__ __forceinline__ void conv_mat(const float* W, int K, int N, bf16_t* WT, int Kp, int Np, LAS float* scr, int gw, int ngw, int lane) {
;     ...
;     if (gw < nitems) CONV_LOAD(gw);
;     for (int item = gw; item < nitems; item += ngw) {
;         const int kb = item / nblk, nb = item % nblk, k0 = 64 * kb, n0 = 32 * nb;
; #pragma unroll
;         for (int i = 0; i < 8; ++i) { const int kk = 8 * i + (lane >> 3), n4 = (lane & 7) * 4; LAS float* d = scr + kk * 33 + n4; d[0] = nv[i][0]; d[1] = nv[i][1]; d[2] = nv[i][2]; d[3] = nv[i][3]; }
;         if (item + ngw < nitems) CONV_LOAD(item + ngw);
;         asm volatile("s_waitcnt lgkmcnt(0)" ::: "memory");
;         const int c = lane & 7;
; #pragma unroll
;         for (int j = 0; j < 4; ++j) { const int n = (lane >> 3) + 8 * j; const LAS float* s = scr + (8 * c) * 33 + n;
;             u32x4 o; o.x = pk2(s[0 * 33], s[1 * 33]); o.y = pk2(s[2 * 33], s[3 * 33]); o.z = pk2(s[4 * 33], s[5 * 33]); o.w = pk2(s[6 * 33], s[7 * 33]);
;             *(u32x4*)(WT + (size_t)(n0 + n) * Kp + k0 + 8 * c) = o; }
.LBB0_524:
	v_add_u32_e32 v36, 0x420, v43
	s_waitcnt vmcnt(4)
	ds_write2_b32 v43, v8, v9 offset1:1
	ds_write2_b32 v43, v10, v11 offset0:2 offset1:3
	ds_write2_b32 v36, v4, v5 offset1:1
	v_add_u32_e32 v36, 0x428, v43
	ds_write2_b32 v36, v6, v7 offset1:1
	v_add_u32_e32 v36, 0x840, v43
	ds_write2_b32 v36, v16, v17 offset1:1
	v_add_u32_e32 v36, 0x848, v43
	ds_write2_b32 v36, v18, v19 offset1:1
	v_add_u32_e32 v36, 0xc60, v43
	ds_write2_b32 v36, v12, v13 offset1:1
	v_add_u32_e32 v36, 0xc68, v43
	ds_write2_b32 v36, v14, v15 offset1:1
	v_add_u32_e32 v36, 0x1080, v43
	ds_write2_b32 v36, v24, v25 offset1:1
	v_add_u32_e32 v36, 0x1088, v43
	ds_write2_b32 v36, v26, v27 offset1:1
	v_add_u32_e32 v36, 0x14a0, v43
	ds_write2_b32 v36, v20, v21 offset1:1
	v_add_u32_e32 v36, 0x14a8, v43
	ds_write2_b32 v36, v22, v23 offset1:1
	v_add_u32_e32 v36, 0x18c0, v43
	s_add_i32 s16, s15, s18
	ds_write2_b32 v36, v32, v33 offset1:1
	v_add_u32_e32 v36, 0x18c8, v43
	s_cmpk_gt_i32 s16, 0xff
	ds_write2_b32 v36, v34, v35 offset1:1
	v_add_u32_e32 v36, 0x1ce0, v43
	s_cselect_b64 s[4:5], -1, 0
	ds_write2_b32 v36, v28, v29 offset1:1
	v_add_u32_e32 v36, 0x1ce8, v43
	s_and_b64 vcc, exec, s[4:5]
	ds_write2_b32 v36, v30, v31 offset1:1
	s_cbranch_vccnz .LBB0_523
	s_ashr_i32 s10, s16, 31
	s_lshr_b32 s10, s10, 26
	s_add_i32 s10, s16, s10
	s_and_b32 s11, s10, 0xffffffc0
	s_lshl_b32 s10, s10, 5
	v_add_u32_e32 v4, s14, v42
	s_and_b32 s10, s10, 0xfffff800
	v_subrev_u32_e32 v4, s10, v4
	v_or_b32_e32 v30, s11, v41
	v_ashrrev_i32_e32 v5, 31, v4
	v_lshl_add_u64 v[36:37], v[4:5], 2, s[2:3]
	v_cmp_gt_i32_e32 vcc, 64, v30
	v_mov_b32_e32 v4, 0
	v_mov_b32_e32 v8, 0
	v_mov_b32_e32 v9, 0
	v_mov_b32_e32 v10, 0
	v_mov_b32_e32 v11, 0
	s_and_saveexec_b64 s[10:11], vcc
	s_cbranch_execz .LBB0_527
	v_ashrrev_i32_e32 v31, 31, v30
	v_lshlrev_b64 v[6:7], 13, v[30:31]
	v_lshl_add_u64 v[6:7], v[36:37], 0, v[6:7]
	global_load_dwordx4 v[8:11], v[6:7], off

; #define LAS __attribute__((address_space(3)))
; #define CONV_LOAD(it_) do { const int kb_ = (it_) / nblk, nb_ = (it_) % nblk; _Pragma("unroll") for (int i = 0; i < 8; ++i) { const int k_ = 64 * kb_ + 8 * i + (lane >> 3), n_ = 32 * nb_ + (lane & 7) * 4; \
;         nv[i] = (k_ < K && 32 * nb_ < N) ? *(const f32x4*)(W + (size_t)k_ * N + n_) : (f32x4){0.f, 0.f, 0.f, 0.f}; } } while (0)
; __device__ __forceinline__ void conv_mat(const float* W, int K, int N, bf16_t* WT, int Kp, int Np, LAS float* scr, int gw, int ngw, int lane) {
;     ...
;     if (gw < nitems) CONV_LOAD(gw);
;     for (int item = gw; item < nitems; item += ngw) {
;         const int kb = item / nblk, nb = item % nblk, k0 = 64 * kb, n0 = 32 * nb;
; #pragma unroll
;         for (int i = 0; i < 8; ++i) { const int kk = 8 * i + (lane >> 3), n4 = (lane & 7) * 4; LAS float* d = scr + kk * 33 + n4; d[0] = nv[i][0]; d[1] = nv[i][1]; d[2] = nv[i][2]; d[3] = nv[i][3]; }
;         if (item + ngw < nitems) CONV_LOAD(item + ngw);
;         asm volatile("s_waitcnt lgkmcnt(0)" ::: "memory");
;         const int c = lane & 7;
; #pragma unroll
;         for (int j = 0; j < 4; ++j) { const int n = (lane >> 3) + 8 * j; const LAS float* s = scr + (8 * c) * 33 + n;
.LBB0_560:
	s_or_b64 exec, exec, s[4:5]
	v_lshlrev_b32_e32 v0, 3, v40
	v_and_b32_e32 v0, 56, v0
	v_readlane_b32 s4, v235, 6
	v_lshlrev_b32_e32 v2, 1, v0
	v_readlane_b32 s5, v235, 7
	v_lshl_add_u32 v37, v36, 2, s20
	v_mul_u32_u24_e32 v39, 0x84, v0
	v_lshl_add_u64 v[0:1], s[4:5], 0, v[2:3]
	v_lshlrev_b32_e32 v2, 2, v38
	v_mul_u32_u24_e32 v41, 0x84, v38
	s_lshl_b32 s10, s19, 5
	s_lshl_b32 s11, s18, 5
	v_add3_u32 v2, s20, v39, v2
	v_or_b32_e32 v39, s10, v36
	v_add_u32_e32 v41, v37, v41
	s_mov_b32 s12, s11
	v_mov_b32_e32 v42, v38
	s_mov_b32 s13, s19
	s_waitcnt vmcnt(0)
	s_branch .LBB0_563

; #define LAS __attribute__((address_space(3)))
; __device__ __forceinline__ unsigned pk2(float lo, float hi) { f32x2c v = {lo, hi}; return __builtin_bit_cast(unsigned, __builtin_convertvector(v, bf16x2c)); }
; #define CONV_LOAD(it_) do { const int kb_ = (it_) / nblk, nb_ = (it_) % nblk; _Pragma("unroll") for (int i = 0; i < 8; ++i) { const int k_ = 64 * kb_ + 8 * i + (lane >> 3), n_ = 32 * nb_ + (lane & 7) * 4; \
;         nv[i] = (k_ < K && 32 * nb_ < N) ? *(const f32x4*)(W + (size_t)k_ * N + n_) : (f32x4){0.f, 0.f, 0.f, 0.f}; } } while (0)
; __device__ __forceinline__ void conv_mat(const float* W, int K, int N, bf16_t* WT, int Kp, int Np, LAS float* scr, int gw, int ngw, int lane) {
;     ...
;     if (gw < nitems) CONV_LOAD(gw);
;     for (int item = gw; item < nitems; item += ngw) {
;         const int kb = item / nblk, nb = item % nblk, k0 = 64 * kb, n0 = 32 * nb;
; #pragma unroll
;         for (int i = 0; i < 8; ++i) { const int kk = 8 * i + (lane >> 3), n4 = (lane & 7) * 4; LAS float* d = scr + kk * 33 + n4; d[0] = nv[i][0]; d[1] = nv[i][1]; d[2] = nv[i][2]; d[3] = nv[i][3]; }
;         if (item + ngw < nitems) CONV_LOAD(item + ngw);
;         asm volatile("s_waitcnt lgkmcnt(0)" ::: "memory");
;         const int c = lane & 7;
; #pragma unroll
;         for (int j = 0; j < 4; ++j) { const int n = (lane >> 3) + 8 * j; const LAS float* s = scr + (8 * c) * 33 + n;
;             u32x4 o; o.x = pk2(s[0 * 33], s[1 * 33]); o.y = pk2(s[2 * 33], s[3 * 33]); o.z = pk2(s[4 * 33], s[5 * 33]); o.w = pk2(s[6 * 33], s[7 * 33]);
;             *(u32x4*)(WT + (size_t)(n0 + n) * Kp + k0 + 8 * c) = o; }
.LBB0_563:
	v_add_u32_e32 v36, 0x420, v41
	s_waitcnt vmcnt(4)
	ds_write2_b32 v41, v8, v9 offset1:1
	ds_write2_b32 v41, v10, v11 offset0:2 offset1:3
	ds_write2_b32 v36, v4, v5 offset1:1
	v_add_u32_e32 v36, 0x428, v41
	ds_write2_b32 v36, v6, v7 offset1:1
	v_add_u32_e32 v36, 0x840, v41
	ds_write2_b32 v36, v16, v17 offset1:1
	v_add_u32_e32 v36, 0x848, v41
	ds_write2_b32 v36, v18, v19 offset1:1
	v_add_u32_e32 v36, 0xc60, v41
	ds_write2_b32 v36, v12, v13 offset1:1
	v_add_u32_e32 v36, 0xc68, v41
	ds_write2_b32 v36, v14, v15 offset1:1
	v_add_u32_e32 v36, 0x1080, v41
	ds_write2_b32 v36, v24, v25 offset1:1
	v_add_u32_e32 v36, 0x1088, v41
	ds_write2_b32 v36, v26, v27 offset1:1
	v_add_u32_e32 v36, 0x14a0, v41
	ds_write2_b32 v36, v20, v21 offset1:1
	v_add_u32_e32 v36, 0x14a8, v41
	ds_write2_b32 v36, v22, v23 offset1:1
	v_add_u32_e32 v36, 0x18c0, v41
	s_add_i32 s14, s13, s18
	ds_write2_b32 v36, v32, v33 offset1:1
	v_add_u32_e32 v36, 0x18c8, v41
	s_cmpk_gt_i32 s14, 0x15ff
	ds_write2_b32 v36, v34, v35 offset1:1
	v_add_u32_e32 v36, 0x1ce0, v41
	s_cselect_b64 s[4:5], -1, 0
	ds_write2_b32 v36, v28, v29 offset1:1
	v_add_u32_e32 v36, 0x1ce8, v41
	s_and_b64 vcc, exec, s[4:5]
	ds_write2_b32 v36, v30, v31 offset1:1
	s_cbranch_vccnz .LBB0_562
	s_mul_hi_i32 s8, s14, 0x2e8ba2e9
	s_lshr_b32 s9, s8, 31
	s_ashr_i32 s8, s8, 5
	s_add_i32 s8, s8, s9
	v_lshl_or_b32 v29, s8, 6, v38
	s_mulk_i32 s8, 0xea00
	s_add_i32 s8, s8, s12
	v_add_u32_e32 v4, s8, v39
	v_ashrrev_i32_e32 v5, 31, v4
	v_lshl_add_u64 v[36:37], v[4:5], 2, s[2:3]
	v_cmp_gt_i32_e32 vcc, s50, v29
	v_mov_b32_e32 v4, 0
	v_mov_b32_e32 v8, 0
	v_mov_b32_e32 v9, 0
	v_mov_b32_e32 v10, 0
	v_mov_b32_e32 v11, 0
	s_and_saveexec_b64 s[8:9], vcc
	s_cbranch_execz .LBB0_566
	v_mad_i64_i32 v[6:7], s[16:17], v29, s33, v[36:37]
	global_load_dwordx4 v[8:11], v[6:7], off

; #define LAS __attribute__((address_space(3)))
; #define CONV_LOAD(it_) do { const int kb_ = (it_) / nblk, nb_ = (it_) % nblk; _Pragma("unroll") for (int i = 0; i < 8; ++i) { const int k_ = 64 * kb_ + 8 * i + (lane >> 3), n_ = 32 * nb_ + (lane & 7) * 4; \
;         nv[i] = (k_ < K && 32 * nb_ < N) ? *(const f32x4*)(W + (size_t)k_ * N + n_) : (f32x4){0.f, 0.f, 0.f, 0.f}; } } while (0)
; __device__ __forceinline__ void conv_mat(const float* W, int K, int N, bf16_t* WT, int Kp, int Np, LAS float* scr, int gw, int ngw, int lane) {
;     ...
;     if (gw < nitems) CONV_LOAD(gw);
;     for (int item = gw; item < nitems; item += ngw) {
;         const int kb = item / nblk, nb = item % nblk, k0 = 64 * kb, n0 = 32 * nb;
; #pragma unroll
;         for (int i = 0; i < 8; ++i) { const int kk = 8 * i + (lane >> 3), n4 = (lane & 7) * 4; LAS float* d = scr + kk * 33 + n4; d[0] = nv[i][0]; d[1] = nv[i][1]; d[2] = nv[i][2]; d[3] = nv[i][3]; }
;         if (item + ngw < nitems) CONV_LOAD(item + ngw);
;         asm volatile("s_waitcnt lgkmcnt(0)" ::: "memory");
;         const int c = lane & 7;
; #pragma unroll
;         for (int j = 0; j < 4; ++j) { const int n = (lane >> 3) + 8 * j; const LAS float* s = scr + (8 * c) * 33 + n;
.LBB0_598:
	s_or_b64 exec, exec, s[4:5]
	v_lshlrev_b32_e32 v0, 3, v40
	v_and_b32_e32 v0, 56, v0
	v_readlane_b32 s4, v235, 32
	v_lshlrev_b32_e32 v2, 1, v0
	v_readlane_b32 s5, v235, 33
	v_mul_u32_u24_e32 v37, 0x84, v0
	v_lshl_add_u32 v36, v38, 2, s20
	v_lshl_add_u64 v[0:1], s[4:5], 0, v[2:3]
	v_lshlrev_b32_e32 v2, 2, v41
	v_add3_u32 v2, s20, v37, v2
	v_mul_u32_u24_e32 v37, 0x84, v41
	s_lshl_b32 s10, s19, 5
	s_lshl_b32 s11, s18, 5
	v_or_b32_e32 v40, s10, v38
	v_add_u32_e32 v42, v36, v37
	s_mov_b32 s12, s11
	v_mov_b32_e32 v43, v41
	s_waitcnt vmcnt(0)
	s_branch .LBB0_601

; #define LAS __attribute__((address_space(3)))
; __device__ __forceinline__ unsigned pk2(float lo, float hi) { f32x2c v = {lo, hi}; return __builtin_bit_cast(unsigned, __builtin_convertvector(v, bf16x2c)); }
; #define CONV_LOAD(it_) do { const int kb_ = (it_) / nblk, nb_ = (it_) % nblk; _Pragma("unroll") for (int i = 0; i < 8; ++i) { const int k_ = 64 * kb_ + 8 * i + (lane >> 3), n_ = 32 * nb_ + (lane & 7) * 4; \
;         nv[i] = (k_ < K && 32 * nb_ < N) ? *(const f32x4*)(W + (size_t)k_ * N + n_) : (f32x4){0.f, 0.f, 0.f, 0.f}; } } while (0)
; __device__ __forceinline__ void conv_mat(const float* W, int K, int N, bf16_t* WT, int Kp, int Np, LAS float* scr, int gw, int ngw, int lane) {
;     ...
;     if (gw < nitems) CONV_LOAD(gw);
;     for (int item = gw; item < nitems; item += ngw) {
;         const int kb = item / nblk, nb = item % nblk, k0 = 64 * kb, n0 = 32 * nb;
; #pragma unroll
;         for (int i = 0; i < 8; ++i) { const int kk = 8 * i + (lane >> 3), n4 = (lane & 7) * 4; LAS float* d = scr + kk * 33 + n4; d[0] = nv[i][0]; d[1] = nv[i][1]; d[2] = nv[i][2]; d[3] = nv[i][3]; }
;         if (item + ngw < nitems) CONV_LOAD(item + ngw);
;         asm volatile("s_waitcnt lgkmcnt(0)" ::: "memory");
;         const int c = lane & 7;
; #pragma unroll
;         for (int j = 0; j < 4; ++j) { const int n = (lane >> 3) + 8 * j; const LAS float* s = scr + (8 * c) * 33 + n;
;             u32x4 o; o.x = pk2(s[0 * 33], s[1 * 33]); o.y = pk2(s[2 * 33], s[3 * 33]); o.z = pk2(s[4 * 33], s[5 * 33]); o.w = pk2(s[6 * 33], s[7 * 33]);
;             *(u32x4*)(WT + (size_t)(n0 + n) * Kp + k0 + 8 * c) = o; }
.LBB0_601:
	v_add_u32_e32 v36, 0x420, v42
	s_waitcnt vmcnt(4)
	ds_write2_b32 v42, v8, v9 offset1:1
	ds_write2_b32 v42, v10, v11 offset0:2 offset1:3
	ds_write2_b32 v36, v4, v5 offset1:1
	v_add_u32_e32 v36, 0x428, v42
	ds_write2_b32 v36, v6, v7 offset1:1
	v_add_u32_e32 v36, 0x840, v42
	ds_write2_b32 v36, v16, v17 offset1:1
	v_add_u32_e32 v36, 0x848, v42
	ds_write2_b32 v36, v18, v19 offset1:1
	v_add_u32_e32 v36, 0xc60, v42
	ds_write2_b32 v36, v12, v13 offset1:1
	v_add_u32_e32 v36, 0xc68, v42
	ds_write2_b32 v36, v14, v15 offset1:1
	v_add_u32_e32 v36, 0x1080, v42
	ds_write2_b32 v36, v24, v25 offset1:1
	v_add_u32_e32 v36, 0x1088, v42
	ds_write2_b32 v36, v26, v27 offset1:1
	v_add_u32_e32 v36, 0x14a0, v42
	ds_write2_b32 v36, v20, v21 offset1:1
	v_add_u32_e32 v36, 0x14a8, v42
	ds_write2_b32 v36, v22, v23 offset1:1
	v_add_u32_e32 v36, 0x18c0, v42
	s_add_i32 s13, s19, s18
	ds_write2_b32 v36, v32, v33 offset1:1
	v_add_u32_e32 v36, 0x18c8, v42
	s_cmpk_gt_i32 s13, 0x7ff
	ds_write2_b32 v36, v34, v35 offset1:1
	v_add_u32_e32 v36, 0x1ce0, v42
	s_cselect_b64 s[4:5], -1, 0
	ds_write2_b32 v36, v28, v29 offset1:1
	v_add_u32_e32 v36, 0x1ce8, v42
	s_and_b64 vcc, exec, s[4:5]
	ds_write2_b32 v36, v30, v31 offset1:1
	s_cbranch_vccnz .LBB0_600
	s_ashr_i32 s8, s13, 31
	s_lshr_b32 s8, s8, 26
	s_add_i32 s8, s13, s8
	s_and_b32 s9, s8, 0xffffffc0
	s_lshl_b32 s8, s8, 5
	v_add_u32_e32 v4, s12, v40
	s_and_b32 s8, s8, 0xfffff800
	v_subrev_u32_e32 v4, s8, v4
	v_or_b32_e32 v30, s9, v41
	v_ashrrev_i32_e32 v5, 31, v4
	v_lshl_add_u64 v[36:37], v[4:5], 2, s[2:3]
	v_cmp_gt_i32_e32 vcc, s50, v30
	v_mov_b32_e32 v4, 0
	v_mov_b32_e32 v8, 0
	v_mov_b32_e32 v9, 0
	v_mov_b32_e32 v10, 0
	v_mov_b32_e32 v11, 0
	s_and_saveexec_b64 s[8:9], vcc
	s_cbranch_execz .LBB0_604
	v_ashrrev_i32_e32 v31, 31, v30
	v_lshlrev_b64 v[6:7], 13, v[30:31]
	v_lshl_add_u64 v[6:7], v[36:37], 0, v[6:7]
	global_load_dwordx4 v[8:11], v[6:7], off
